# march: G^T tiles kept in registers as the MFMA operand of y (no M^T LDS round trip), Y waves do tiles+y_off in one pass, S waves state only
# speedup vs baseline: 1.0339x; 1.0050x over previous
.Lm_fwd_1:
	s_lshl_b32 s15, s7, 23
	s_lshl_b32 s96, s6, 22
	s_add_u32 s15, s15, s96
	s_lshl_b32 s96, s11, 16
	s_add_u32 s15, s15, s96
	s_add_u32 s15, s15, 0x1b000000
	s_add_u32 s38, s36, s15
	s_addc_u32 s39, s37, 0
	s_lshl_b32 s15, s8, 1
	s_add_u32 s15, s15, s5
	s_lshl_b32 s15, s15, 20
	s_lshl_b32 s96, s6, 19
	s_add_u32 s15, s15, s96
	s_lshl_b32 s96, s11, 13
	s_add_u32 s15, s15, s96
	s_add_u32 s15, s15, 0x17000000
	s_add_u32 s40, s36, s15
	s_addc_u32 s41, s37, 0
	s_lshl_b32 s15, s6, 21
	s_add_u32 s15, s15, s9
	s_lshl_b32 s96, s11, 15
	s_add_u32 s15, s15, s96
	s_add_u32 s15, s15, 0x1f000000
	s_add_u32 s42, s36, s15
	s_addc_u32 s43, s37, 0
	s_lshl_b32 s15, s6, 25
	s_lshl_b32 s96, s8, 7
	s_add_u32 s15, s15, s96
	s_lshl_b32 s96, s5, 6
	s_add_u32 s15, s15, s96
	s_lshl_b32 s96, s11, 19
	s_add_u32 s15, s15, s96
	s_lshl_b32 s96, s51, 26
	s_add_u32 s15, s15, s96
	s_add_u32 s15, s15, 0xf000000
	s_add_u32 s44, s36, s15
	s_addc_u32 s45, s37, 0
	s_add_u32 s4, s3, 1
	s_sub_i32 s5, 4, s3
	s_movk_i32 s6, 0x2200
	s_mov_b32 s7, 0xffffde00
	s_movk_i32 s8, 0x80
	s_mov_b32 s9, 0xffffff80
	s_movk_i32 s15, 0x800
	s_mov_b32 s96, 0xfffff800
	s_cmp_eq_u32 s51, 0
	s_cselect_b32 s52, s4, s5
	s_cselect_b32 s53, s7, s6
	s_cselect_b32 s54, s9, s8
	s_cselect_b32 s13, s96, s15
	s_waitcnt lgkmcnt(0)
	v_mov_b32_e32 v1, s10
	v_mul_f32_e32 v1, 0x3fb8aa3b, v1
	v_exp_f32_e32 v1, v1
	s_nop 0
	v_xor_b32_e32 v1, 0x80000000, v1
	s_nop 0
	v_readfirstlane_b32 s62, v1
	v_and_b32_e32 v116, 31, v175
	v_bfe_u32 v117, v175, 5, 1
	v_bfe_u32 v118, v175, 2, 2
	v_and_b32_e32 v119, 3, v175
	v_bfe_u32 v120, v175, 4, 1
	v_and_b32_e32 v121, 63, v175
	v_lshlrev_b32_e32 v122, 5, v120
	v_lshl_add_u32 v122, v119, 3, v122
	v_lshl_add_u32 v123, v117, 3, v118
	v_lshrrev_b32_e32 v124, 4, v175
	v_and_b32_e32 v125, 15, v175
	v_lshlrev_b32_e32 v125, 4, v125
	v_lshl_add_u32 v164, v124, 9, v125
	v_add_u32_e32 v165, 0x4000, v164
	v_add_u32_e32 v166, 0x8000, v164
	v_add_u32_e32 v167, 0xc000, v164
	v_mad_u32_u24 v169, v124, s59, v125
	v_and_b32_e32 v126, 0xff, v175
	v_lshlrev_b32_e32 v168, 4, v126
	v_add_u32_e32 v202, 0x1000, v168
	v_lshrrev_b32_e32 v126, 2, v126
	v_lshlrev_b32_e32 v127, 4, v119
	v_mad_u32_u24 v127, v126, s60, v127
	v_add_u32_e32 v170, 0x19800, v127
	v_lshlrev_b32_e32 v127, 2, v126
	v_add_u32_e32 v171, 0x23000, v127
	v_mov_b32_e32 v172, 0x23400
	s_lshl_b32 s4, s3, 5
	v_add_u32_e32 v128, s4, v116
	v_lshlrev_b32_e32 v129, 4, v117
	v_mad_u32_u24 v173, v128, s59, v129
	v_mad_u32_u24 v130, v116, s59, v129
	v_add_u32_e32 v210, 0x1e800, v130
	v_lshlrev_b32_e32 v130, 2, v128
	v_add_u32_e32 v211, 0x23000, v130
	v_lshlrev_b32_e32 v130, 3, v117
	v_lshl_add_u32 v212, v128, 12, v130
	v_mad_u32_u24 v130, v123, s60, v122
	v_add_u32_e32 v208, 0x19800, v130
	v_add_u32_e32 v192, 0x1c000, v130
	v_mad_u32_u24 v131, v123, s59, v122
	s_sub_i32 s4, s3, 4
	s_lshl_b32 s4, s4, 6
	v_add_u32_e32 v130, s4, v131
	v_add_u32_e32 v193, 0x8800, v130
	v_lshlrev_b32_e32 v130, 3, v117
	v_mad_u32_u24 v130, v116, s59, v130
	v_add_u32_e32 v130, s4, v130
	v_add_u32_e32 v194, 0x1e800, v130
	v_lshlrev_b32_e32 v195, 9, v121
	v_lshlrev_b32_e32 v130, 3, v121
	v_add_u32_e32 v196, 0x23000, v130
	s_lshl_b32 s4, s3, 7
	s_add_u32 s4, s4, 0x23000
	v_add_u32_e32 v217, s4, v129
	v_lshl_add_u32 v130, v117, 2, v118
	s_lshl_b32 s4, s3, 5
	v_add_u32_e32 v130, s4, v130
	v_mad_u32_u24 v130, v130, s60, v122
	v_add_u32_e32 v222, 0x19800, v130
	v_lshlrev_b32_e32 v129, 2, v117
	s_cmp_eq_u32 s51, 0
	s_cbranch_scc0 .Lm_mbwd_2
	v_add_u32_e32 v130, 0, v129
	v_cmp_le_u32_e64 s[64:65], v130, v116
	v_add_u32_e32 v130, 1, v129
	v_cmp_le_u32_e64 s[66:67], v130, v116
	v_add_u32_e32 v130, 2, v129
	v_cmp_le_u32_e64 s[68:69], v130, v116
	v_add_u32_e32 v130, 3, v129
	v_cmp_le_u32_e64 s[70:71], v130, v116
	v_add_u32_e32 v130, 8, v129
	v_cmp_le_u32_e64 s[72:73], v130, v116
	v_add_u32_e32 v130, 9, v129
	v_cmp_le_u32_e64 s[74:75], v130, v116
	v_add_u32_e32 v130, 10, v129
	v_cmp_le_u32_e64 s[76:77], v130, v116
	v_add_u32_e32 v130, 11, v129
	v_cmp_le_u32_e64 s[78:79], v130, v116
	v_add_u32_e32 v130, 16, v129
	v_cmp_le_u32_e64 s[80:81], v130, v116
	v_add_u32_e32 v130, 17, v129
	v_cmp_le_u32_e64 s[82:83], v130, v116
	v_add_u32_e32 v130, 18, v129
	v_cmp_le_u32_e64 s[84:85], v130, v116
	v_add_u32_e32 v130, 19, v129
	v_cmp_le_u32_e64 s[86:87], v130, v116
	v_add_u32_e32 v130, 24, v129
	v_cmp_le_u32_e64 s[88:89], v130, v116
	v_add_u32_e32 v130, 25, v129
	v_cmp_le_u32_e64 s[90:91], v130, v116
	v_add_u32_e32 v130, 26, v129
	v_cmp_le_u32_e64 s[92:93], v130, v116
	v_add_u32_e32 v130, 27, v129
	v_cmp_le_u32_e64 s[94:95], v130, v116
	s_branch .Lm_mdone_3
.Lm_mbwd_2:
	v_add_u32_e32 v130, 0, v129
	v_cmp_ge_u32_e64 s[64:65], v130, v116
	v_add_u32_e32 v130, 1, v129
	v_cmp_ge_u32_e64 s[66:67], v130, v116
	v_add_u32_e32 v130, 2, v129
	v_cmp_ge_u32_e64 s[68:69], v130, v116
	v_add_u32_e32 v130, 3, v129
	v_cmp_ge_u32_e64 s[70:71], v130, v116
	v_add_u32_e32 v130, 8, v129
	v_cmp_ge_u32_e64 s[72:73], v130, v116
	v_add_u32_e32 v130, 9, v129
	v_cmp_ge_u32_e64 s[74:75], v130, v116
	v_add_u32_e32 v130, 10, v129
	v_cmp_ge_u32_e64 s[76:77], v130, v116
	v_add_u32_e32 v130, 11, v129
	v_cmp_ge_u32_e64 s[78:79], v130, v116
	v_add_u32_e32 v130, 16, v129
	v_cmp_ge_u32_e64 s[80:81], v130, v116
	v_add_u32_e32 v130, 17, v129
	v_cmp_ge_u32_e64 s[82:83], v130, v116
	v_add_u32_e32 v130, 18, v129
	v_cmp_ge_u32_e64 s[84:85], v130, v116
	v_add_u32_e32 v130, 19, v129
	v_cmp_ge_u32_e64 s[86:87], v130, v116
	v_add_u32_e32 v130, 24, v129
	v_cmp_ge_u32_e64 s[88:89], v130, v116
	v_add_u32_e32 v130, 25, v129
	v_cmp_ge_u32_e64 s[90:91], v130, v116
	v_add_u32_e32 v130, 26, v129
	v_cmp_ge_u32_e64 s[92:93], v130, v116
	v_add_u32_e32 v130, 27, v129
	v_cmp_ge_u32_e64 s[94:95], v130, v116

.Lm_loop:
	s_cmp_lt_u32 s3, 4
	s_cbranch_scc0 .Lm_hi_11
	v_mov_b32_e32 v223, v173
	v_mov_b32_e32 v224, v217
	v_mov_b32_e32 v225, v222
	ds_read_b128 v[176:179], v173 offset:0
	ds_read_b128 v[180:183], v173 offset:32
	ds_read_b128 v[184:187], v173 offset:64
	ds_read_b128 v[188:191], v173 offset:96
	ds_read_b128 v[192:195], v173 offset:128
	ds_read_b128 v[196:199], v173 offset:160
	ds_read_b128 v[200:203], v173 offset:192
	ds_read_b128 v[204:207], v173 offset:224
	ds_read_b128 v[148:151], v223 offset:34816
	ds_read_b128 v[152:155], v223 offset:34848
	ds_read_b128 v[156:159], v223 offset:34880
	ds_read_b128 v[160:163], v223 offset:34912
	s_waitcnt lgkmcnt(11)
	s_waitcnt lgkmcnt(3)
	v_mfma_f32_32x32x16_bf16 v[116:131], v[148:151], v[176:179], 0
	ds_read_b128 v[148:151], v223 offset:34944
	global_load_dwordx4 v[4:7], v164, s[38:39]
	s_waitcnt lgkmcnt(3)
	v_mfma_f32_32x32x16_bf16 v[116:131], v[152:155], v[180:183], v[116:131]
	ds_read_b128 v[152:155], v223 offset:34976
	global_load_dwordx4 v[20:23], v164, s[38:39] offset:256
	s_waitcnt lgkmcnt(3)
	v_mfma_f32_32x32x16_bf16 v[116:131], v[156:159], v[184:187], v[116:131]
	ds_read_b128 v[156:159], v223 offset:35008
	global_load_dwordx4 v[8:11], v165, s[38:39]
	s_waitcnt lgkmcnt(3)
	v_mfma_f32_32x32x16_bf16 v[116:131], v[160:163], v[188:191], v[116:131]
	ds_read_b128 v[160:163], v223 offset:35040
	global_load_dwordx4 v[24:27], v165, s[38:39] offset:256
	ds_read_b128 v[234:237], v224 offset:0
	ds_read_b128 v[238:241], v224 offset:32
	ds_read_b128 v[242:245], v224 offset:64
	ds_read_b128 v[246:249], v224 offset:96
	ds_read_b32 v250, v211 offset:0
	s_waitcnt lgkmcnt(8)
	v_mfma_f32_32x32x16_bf16 v[116:131], v[148:151], v[192:195], v[116:131]
	global_load_dwordx4 v[12:15], v166, s[38:39]
	s_waitcnt lgkmcnt(7)
	v_mfma_f32_32x32x16_bf16 v[116:131], v[152:155], v[196:199], v[116:131]
	global_load_dwordx4 v[28:31], v166, s[38:39] offset:256
	s_waitcnt lgkmcnt(6)
	v_mfma_f32_32x32x16_bf16 v[116:131], v[156:159], v[200:203], v[116:131]
	global_load_dwordx4 v[16:19], v167, s[38:39]
	s_waitcnt lgkmcnt(5)
	v_mfma_f32_32x32x16_bf16 v[116:131], v[160:163], v[204:207], v[116:131]
	global_load_dwordx4 v[32:35], v167, s[38:39] offset:256
	s_add_u32 s38, s38, s46
	s_addc_u32 s39, s39, s55
	s_add_u32 s40, s40, s47
	s_addc_u32 s41, s41, s55
	s_cmp_eq_u32 s52, 1
	s_cbranch_scc1 .Lm_yfin1_14
	ds_read_b64_tr_b16 v[36:37], v225 offset:0
	ds_read_b64_tr_b16 v[38:39], v225 offset:512
	ds_read_b64_tr_b16 v[72:73], v225 offset:1024
	ds_read_b64_tr_b16 v[74:75], v225 offset:1536
	v_add_u32_e32 v223, s53, v223
	v_add_u32_e32 v224, s54, v224
	v_add_u32_e32 v225, s13, v225
	ds_read_b128 v[148:151], v223 offset:34816
	ds_read_b128 v[152:155], v223 offset:34848
	ds_read_b128 v[156:159], v223 offset:34880
	ds_read_b128 v[160:163], v223 offset:34912
	s_waitcnt lgkmcnt(9)
	s_waitcnt lgkmcnt(8)
	s_waitcnt lgkmcnt(3)
	v_mfma_f32_32x32x16_bf16 v[132:147], v[148:151], v[176:179], 0
	ds_read_b128 v[148:151], v223 offset:34944
	v_sub_f32_e32 v234, v250, v234
	v_sub_f32_e32 v235, v250, v235
	v_sub_f32_e32 v236, v250, v236
	v_sub_f32_e32 v237, v250, v237
	v_sub_f32_e32 v238, v250, v238
	v_sub_f32_e32 v239, v250, v239
	v_sub_f32_e32 v240, v250, v240
	v_sub_f32_e32 v241, v250, v241
	v_sub_f32_e32 v242, v250, v242
	s_waitcnt lgkmcnt(3)
	v_mfma_f32_32x32x16_bf16 v[132:147], v[152:155], v[180:183], v[132:147]
	ds_read_b128 v[152:155], v223 offset:34976
	v_sub_f32_e32 v243, v250, v243
	v_sub_f32_e32 v244, v250, v244
	v_sub_f32_e32 v245, v250, v245
	v_sub_f32_e32 v246, v250, v246
	v_sub_f32_e32 v247, v250, v247
	v_sub_f32_e32 v248, v250, v248
	v_sub_f32_e32 v249, v250, v249
	v_exp_f32_e32 v234, v234
	v_exp_f32_e32 v235, v235
	s_waitcnt lgkmcnt(3)
	v_mfma_f32_32x32x16_bf16 v[132:147], v[156:159], v[184:187], v[132:147]
	ds_read_b128 v[156:159], v223 offset:35008
	v_exp_f32_e32 v236, v236
	v_exp_f32_e32 v237, v237
	v_exp_f32_e32 v238, v238
	v_exp_f32_e32 v239, v239
	v_exp_f32_e32 v240, v240
	v_exp_f32_e32 v241, v241
	v_exp_f32_e32 v242, v242
	v_exp_f32_e32 v243, v243
	v_exp_f32_e32 v244, v244
	s_waitcnt lgkmcnt(3)
	v_mfma_f32_32x32x16_bf16 v[132:147], v[160:163], v[188:191], v[132:147]
	ds_read_b128 v[160:163], v223 offset:35040
	v_exp_f32_e32 v245, v245
	v_exp_f32_e32 v246, v246
	v_exp_f32_e32 v247, v247
	v_exp_f32_e32 v248, v248
	v_exp_f32_e32 v249, v249
	v_mul_f32_e32 v116, v116, v234
	v_mul_f32_e32 v117, v117, v235
	v_mul_f32_e32 v118, v118, v236
	v_mul_f32_e32 v119, v119, v237
	s_waitcnt lgkmcnt(3)
	v_mfma_f32_32x32x16_bf16 v[132:147], v[148:151], v[192:195], v[132:147]
	v_mul_f32_e32 v120, v120, v238
	v_mul_f32_e32 v121, v121, v239
	v_mul_f32_e32 v122, v122, v240
	v_mul_f32_e32 v123, v123, v241
	v_mul_f32_e32 v124, v124, v242
	v_mul_f32_e32 v125, v125, v243
	v_mul_f32_e32 v126, v126, v244
	v_mul_f32_e32 v127, v127, v245
	v_mul_f32_e32 v128, v128, v246
	s_waitcnt lgkmcnt(2)
	v_mfma_f32_32x32x16_bf16 v[132:147], v[152:155], v[196:199], v[132:147]
	v_mul_f32_e32 v129, v129, v247
	v_mul_f32_e32 v130, v130, v248
	v_mul_f32_e32 v131, v131, v249
	v_cndmask_b32_e64 v116, 0, v116, s[64:65]
	v_cndmask_b32_e64 v117, 0, v117, s[66:67]
	v_cndmask_b32_e64 v118, 0, v118, s[68:69]
	v_cndmask_b32_e64 v119, 0, v119, s[70:71]
	v_cndmask_b32_e64 v120, 0, v120, s[72:73]
	v_cndmask_b32_e64 v121, 0, v121, s[74:75]
	s_waitcnt lgkmcnt(1)
	v_mfma_f32_32x32x16_bf16 v[132:147], v[156:159], v[200:203], v[132:147]
	v_cndmask_b32_e64 v122, 0, v122, s[76:77]
	v_cndmask_b32_e64 v123, 0, v123, s[78:79]
	v_cndmask_b32_e64 v124, 0, v124, s[80:81]
	v_cndmask_b32_e64 v125, 0, v125, s[82:83]
	v_cndmask_b32_e64 v126, 0, v126, s[84:85]
	v_cndmask_b32_e64 v127, 0, v127, s[86:87]
	v_cndmask_b32_e64 v128, 0, v128, s[88:89]
	v_cndmask_b32_e64 v129, 0, v129, s[90:91]
	v_cndmask_b32_e64 v130, 0, v130, s[92:93]
	s_waitcnt lgkmcnt(0)
	v_mfma_f32_32x32x16_bf16 v[132:147], v[160:163], v[204:207], v[132:147]
	v_cndmask_b32_e64 v131, 0, v131, s[94:95]
	v_cvt_pk_bf16_f32 v116, v116, v117
	v_cvt_pk_bf16_f32 v117, v118, v119
	v_cvt_pk_bf16_f32 v118, v120, v121
	v_cvt_pk_bf16_f32 v119, v122, v123
	v_cvt_pk_bf16_f32 v120, v124, v125
	v_cvt_pk_bf16_f32 v121, v126, v127
	v_cvt_pk_bf16_f32 v122, v128, v129
	v_cvt_pk_bf16_f32 v123, v130, v131
	ds_read_b128 v[234:237], v224 offset:0
	ds_read_b128 v[238:241], v224 offset:32
	ds_read_b128 v[242:245], v224 offset:64
	ds_read_b128 v[246:249], v224 offset:96
	v_mfma_f32_32x32x16_bf16 v[76:91], v[36:39], v[116:119], 0
	v_mfma_f32_32x32x16_bf16 v[76:91], v[72:75], v[120:123], v[76:91]
	s_cmp_eq_u32 s52, 2
	s_cbranch_scc1 .Lm_yfin2_15
	ds_read_b64_tr_b16 v[36:37], v225 offset:0
	ds_read_b64_tr_b16 v[38:39], v225 offset:512
	ds_read_b64_tr_b16 v[72:73], v225 offset:1024
	ds_read_b64_tr_b16 v[74:75], v225 offset:1536
	v_add_u32_e32 v223, s53, v223
	v_add_u32_e32 v224, s54, v224
	v_add_u32_e32 v225, s13, v225
	ds_read_b128 v[148:151], v223 offset:34816
	ds_read_b128 v[152:155], v223 offset:34848
	ds_read_b128 v[156:159], v223 offset:34880
	ds_read_b128 v[160:163], v223 offset:34912
	s_waitcnt lgkmcnt(8)
	s_waitcnt lgkmcnt(3)
	v_mfma_f32_32x32x16_bf16 v[116:131], v[148:151], v[176:179], 0
	ds_read_b128 v[148:151], v223 offset:34944
	v_sub_f32_e32 v234, v250, v234
	v_sub_f32_e32 v235, v250, v235
	v_sub_f32_e32 v236, v250, v236
	v_sub_f32_e32 v237, v250, v237
	v_sub_f32_e32 v238, v250, v238
	v_sub_f32_e32 v239, v250, v239
	v_sub_f32_e32 v240, v250, v240
	s_waitcnt lgkmcnt(3)
	v_mfma_f32_32x32x16_bf16 v[116:131], v[152:155], v[180:183], v[116:131]
	ds_read_b128 v[152:155], v223 offset:34976
	v_sub_f32_e32 v241, v250, v241
	v_sub_f32_e32 v242, v250, v242
	v_sub_f32_e32 v243, v250, v243
	v_sub_f32_e32 v244, v250, v244
	v_sub_f32_e32 v245, v250, v245
	v_sub_f32_e32 v246, v250, v246
	v_sub_f32_e32 v247, v250, v247
	s_waitcnt lgkmcnt(3)
	v_mfma_f32_32x32x16_bf16 v[116:131], v[156:159], v[184:187], v[116:131]
	ds_read_b128 v[156:159], v223 offset:35008
	v_sub_f32_e32 v248, v250, v248
	v_sub_f32_e32 v249, v250, v249
	v_exp_f32_e32 v234, v234
	v_exp_f32_e32 v235, v235
	v_exp_f32_e32 v236, v236
	v_exp_f32_e32 v237, v237
	v_exp_f32_e32 v238, v238
	s_waitcnt lgkmcnt(3)
	v_mfma_f32_32x32x16_bf16 v[116:131], v[160:163], v[188:191], v[116:131]
	ds_read_b128 v[160:163], v223 offset:35040
	v_exp_f32_e32 v239, v239
	v_exp_f32_e32 v240, v240
	v_exp_f32_e32 v241, v241
	v_exp_f32_e32 v242, v242
	v_exp_f32_e32 v243, v243
	v_exp_f32_e32 v244, v244
	v_exp_f32_e32 v245, v245
	s_waitcnt lgkmcnt(3)
	v_mfma_f32_32x32x16_bf16 v[116:131], v[148:151], v[192:195], v[116:131]
	v_exp_f32_e32 v246, v246
	v_exp_f32_e32 v247, v247
	v_exp_f32_e32 v248, v248
	v_exp_f32_e32 v249, v249
	v_mul_f32_e32 v132, v132, v234
	v_mul_f32_e32 v133, v133, v235
	v_mul_f32_e32 v134, v134, v236
	s_waitcnt lgkmcnt(2)
	v_mfma_f32_32x32x16_bf16 v[116:131], v[152:155], v[196:199], v[116:131]
	v_mul_f32_e32 v135, v135, v237
	v_mul_f32_e32 v136, v136, v238
	v_mul_f32_e32 v137, v137, v239
	v_mul_f32_e32 v138, v138, v240
	v_mul_f32_e32 v139, v139, v241
	v_mul_f32_e32 v140, v140, v242
	v_mul_f32_e32 v141, v141, v243
	s_waitcnt lgkmcnt(1)
	v_mfma_f32_32x32x16_bf16 v[116:131], v[156:159], v[200:203], v[116:131]
	v_mul_f32_e32 v142, v142, v244
	v_mul_f32_e32 v143, v143, v245
	v_mul_f32_e32 v144, v144, v246
	v_mul_f32_e32 v145, v145, v247
	v_mul_f32_e32 v146, v146, v248
	v_mul_f32_e32 v147, v147, v249
	v_cvt_pk_bf16_f32 v132, v132, v133
	s_waitcnt lgkmcnt(0)
	v_mfma_f32_32x32x16_bf16 v[116:131], v[160:163], v[204:207], v[116:131]
	v_cvt_pk_bf16_f32 v133, v134, v135
	v_cvt_pk_bf16_f32 v134, v136, v137
	v_cvt_pk_bf16_f32 v135, v138, v139
	v_cvt_pk_bf16_f32 v136, v140, v141
	v_cvt_pk_bf16_f32 v137, v142, v143
	v_cvt_pk_bf16_f32 v138, v144, v145
	v_cvt_pk_bf16_f32 v139, v146, v147
	ds_read_b128 v[234:237], v224 offset:0
	ds_read_b128 v[238:241], v224 offset:32
	ds_read_b128 v[242:245], v224 offset:64
	ds_read_b128 v[246:249], v224 offset:96
	v_mfma_f32_32x32x16_bf16 v[76:91], v[36:39], v[132:135], v[76:91]
	v_mfma_f32_32x32x16_bf16 v[76:91], v[72:75], v[136:139], v[76:91]
	s_cmp_eq_u32 s52, 3
	s_cbranch_scc1 .Lm_yfin3_16
	ds_read_b64_tr_b16 v[36:37], v225 offset:0
	ds_read_b64_tr_b16 v[38:39], v225 offset:512
	ds_read_b64_tr_b16 v[72:73], v225 offset:1024
	ds_read_b64_tr_b16 v[74:75], v225 offset:1536
	v_add_u32_e32 v223, s53, v223
	v_add_u32_e32 v224, s54, v224
	v_add_u32_e32 v225, s13, v225
	ds_read_b128 v[148:151], v223 offset:34816
	ds_read_b128 v[152:155], v223 offset:34848
	ds_read_b128 v[156:159], v223 offset:34880
	ds_read_b128 v[160:163], v223 offset:34912
	s_waitcnt lgkmcnt(8)
	s_waitcnt lgkmcnt(3)
	v_mfma_f32_32x32x16_bf16 v[132:147], v[148:151], v[176:179], 0
	ds_read_b128 v[148:151], v223 offset:34944
	v_sub_f32_e32 v234, v250, v234
	v_sub_f32_e32 v235, v250, v235
	v_sub_f32_e32 v236, v250, v236
	v_sub_f32_e32 v237, v250, v237
	v_sub_f32_e32 v238, v250, v238
	v_sub_f32_e32 v239, v250, v239
	v_sub_f32_e32 v240, v250, v240
	s_waitcnt lgkmcnt(3)
	v_mfma_f32_32x32x16_bf16 v[132:147], v[152:155], v[180:183], v[132:147]
	ds_read_b128 v[152:155], v223 offset:34976
	v_sub_f32_e32 v241, v250, v241
	v_sub_f32_e32 v242, v250, v242
	v_sub_f32_e32 v243, v250, v243
	v_sub_f32_e32 v244, v250, v244
	v_sub_f32_e32 v245, v250, v245
	v_sub_f32_e32 v246, v250, v246
	v_sub_f32_e32 v247, v250, v247
	s_waitcnt lgkmcnt(3)
	v_mfma_f32_32x32x16_bf16 v[132:147], v[156:159], v[184:187], v[132:147]
	ds_read_b128 v[156:159], v223 offset:35008
	v_sub_f32_e32 v248, v250, v248
	v_sub_f32_e32 v249, v250, v249
	v_exp_f32_e32 v234, v234
	v_exp_f32_e32 v235, v235
	v_exp_f32_e32 v236, v236
	v_exp_f32_e32 v237, v237
	v_exp_f32_e32 v238, v238
	s_waitcnt lgkmcnt(3)
	v_mfma_f32_32x32x16_bf16 v[132:147], v[160:163], v[188:191], v[132:147]
	ds_read_b128 v[160:163], v223 offset:35040
	v_exp_f32_e32 v239, v239
	v_exp_f32_e32 v240, v240
	v_exp_f32_e32 v241, v241
	v_exp_f32_e32 v242, v242
	v_exp_f32_e32 v243, v243
	v_exp_f32_e32 v244, v244
	v_exp_f32_e32 v245, v245
	s_waitcnt lgkmcnt(3)
	v_mfma_f32_32x32x16_bf16 v[132:147], v[148:151], v[192:195], v[132:147]
	v_exp_f32_e32 v246, v246
	v_exp_f32_e32 v247, v247
	v_exp_f32_e32 v248, v248
	v_exp_f32_e32 v249, v249
	v_mul_f32_e32 v116, v116, v234
	v_mul_f32_e32 v117, v117, v235
	v_mul_f32_e32 v118, v118, v236
	s_waitcnt lgkmcnt(2)
	v_mfma_f32_32x32x16_bf16 v[132:147], v[152:155], v[196:199], v[132:147]
	v_mul_f32_e32 v119, v119, v237
	v_mul_f32_e32 v120, v120, v238
	v_mul_f32_e32 v121, v121, v239
	v_mul_f32_e32 v122, v122, v240
	v_mul_f32_e32 v123, v123, v241
	v_mul_f32_e32 v124, v124, v242
	v_mul_f32_e32 v125, v125, v243
	s_waitcnt lgkmcnt(1)
	v_mfma_f32_32x32x16_bf16 v[132:147], v[156:159], v[200:203], v[132:147]
	v_mul_f32_e32 v126, v126, v244
	v_mul_f32_e32 v127, v127, v245
	v_mul_f32_e32 v128, v128, v246
	v_mul_f32_e32 v129, v129, v247
	v_mul_f32_e32 v130, v130, v248
	v_mul_f32_e32 v131, v131, v249
	v_cvt_pk_bf16_f32 v116, v116, v117
	s_waitcnt lgkmcnt(0)
	v_mfma_f32_32x32x16_bf16 v[132:147], v[160:163], v[204:207], v[132:147]
	v_cvt_pk_bf16_f32 v117, v118, v119
	v_cvt_pk_bf16_f32 v118, v120, v121
	v_cvt_pk_bf16_f32 v119, v122, v123
	v_cvt_pk_bf16_f32 v120, v124, v125
	v_cvt_pk_bf16_f32 v121, v126, v127
	v_cvt_pk_bf16_f32 v122, v128, v129
	v_cvt_pk_bf16_f32 v123, v130, v131
	ds_read_b128 v[234:237], v224 offset:0
	ds_read_b128 v[238:241], v224 offset:32
	ds_read_b128 v[242:245], v224 offset:64
	ds_read_b128 v[246:249], v224 offset:96
	v_mfma_f32_32x32x16_bf16 v[76:91], v[36:39], v[116:119], v[76:91]
	v_mfma_f32_32x32x16_bf16 v[76:91], v[72:75], v[120:123], v[76:91]
	ds_read_b64_tr_b16 v[36:37], v225 offset:0
	ds_read_b64_tr_b16 v[38:39], v225 offset:512
	ds_read_b64_tr_b16 v[72:73], v225 offset:1024
	ds_read_b64_tr_b16 v[74:75], v225 offset:1536
	s_waitcnt lgkmcnt(4)
	ds_read_b128 v[148:151], v210 offset:0
	ds_read_b128 v[152:155], v210 offset:32
	ds_read_b128 v[156:159], v210 offset:64
	ds_read_b128 v[160:163], v210 offset:96
	s_waitcnt lgkmcnt(3)
	v_mfma_f32_32x32x16_bf16 v[92:107], v[148:151], v[176:179], 0
	ds_read_b128 v[148:151], v210 offset:128
	v_sub_f32_e32 v234, v250, v234
	v_sub_f32_e32 v235, v250, v235
	v_sub_f32_e32 v236, v250, v236
	v_sub_f32_e32 v237, v250, v237
	v_sub_f32_e32 v238, v250, v238
	v_sub_f32_e32 v239, v250, v239
	v_sub_f32_e32 v240, v250, v240
	s_waitcnt lgkmcnt(3)
	v_mfma_f32_32x32x16_bf16 v[92:107], v[152:155], v[180:183], v[92:107]
	ds_read_b128 v[152:155], v210 offset:160
	v_sub_f32_e32 v241, v250, v241
	v_sub_f32_e32 v242, v250, v242
	v_sub_f32_e32 v243, v250, v243
	v_sub_f32_e32 v244, v250, v244
	v_sub_f32_e32 v245, v250, v245
	v_sub_f32_e32 v246, v250, v246
	v_sub_f32_e32 v247, v250, v247
	s_waitcnt lgkmcnt(3)
	v_mfma_f32_32x32x16_bf16 v[92:107], v[156:159], v[184:187], v[92:107]
	ds_read_b128 v[156:159], v210 offset:192
	v_sub_f32_e32 v248, v250, v248
	v_sub_f32_e32 v249, v250, v249
	v_exp_f32_e32 v234, v234
	v_exp_f32_e32 v235, v235
	v_exp_f32_e32 v236, v236
	v_exp_f32_e32 v237, v237
	v_exp_f32_e32 v238, v238
	s_waitcnt lgkmcnt(3)
	v_mfma_f32_32x32x16_bf16 v[92:107], v[160:163], v[188:191], v[92:107]
	ds_read_b128 v[160:163], v210 offset:224
	v_exp_f32_e32 v239, v239
	v_exp_f32_e32 v240, v240
	v_exp_f32_e32 v241, v241
	v_exp_f32_e32 v242, v242
	v_exp_f32_e32 v243, v243
	v_exp_f32_e32 v244, v244
	v_exp_f32_e32 v245, v245
	s_waitcnt lgkmcnt(3)
	v_mfma_f32_32x32x16_bf16 v[92:107], v[148:151], v[192:195], v[92:107]
	v_exp_f32_e32 v246, v246
	v_exp_f32_e32 v247, v247
	v_exp_f32_e32 v248, v248
	v_exp_f32_e32 v249, v249
	v_mul_f32_e32 v132, v132, v234
	v_mul_f32_e32 v133, v133, v235
	v_mul_f32_e32 v134, v134, v236
	s_waitcnt lgkmcnt(2)
	v_mfma_f32_32x32x16_bf16 v[92:107], v[152:155], v[196:199], v[92:107]
	v_mul_f32_e32 v135, v135, v237
	v_mul_f32_e32 v136, v136, v238
	v_mul_f32_e32 v137, v137, v239
	v_mul_f32_e32 v138, v138, v240
	v_mul_f32_e32 v139, v139, v241
	v_mul_f32_e32 v140, v140, v242
	v_mul_f32_e32 v141, v141, v243
	s_waitcnt lgkmcnt(1)
	v_mfma_f32_32x32x16_bf16 v[92:107], v[156:159], v[200:203], v[92:107]
	v_mul_f32_e32 v142, v142, v244
	v_mul_f32_e32 v143, v143, v245
	v_mul_f32_e32 v144, v144, v246
	v_mul_f32_e32 v145, v145, v247
	v_mul_f32_e32 v146, v146, v248
	v_mul_f32_e32 v147, v147, v249
	v_cvt_pk_bf16_f32 v132, v132, v133
	s_waitcnt lgkmcnt(0)
	v_mfma_f32_32x32x16_bf16 v[92:107], v[160:163], v[204:207], v[92:107]
	v_cvt_pk_bf16_f32 v133, v134, v135
	v_cvt_pk_bf16_f32 v134, v136, v137
	v_cvt_pk_bf16_f32 v135, v138, v139
	v_cvt_pk_bf16_f32 v136, v140, v141
	v_cvt_pk_bf16_f32 v137, v142, v143
	v_cvt_pk_bf16_f32 v138, v144, v145
	v_cvt_pk_bf16_f32 v139, v146, v147
	v_mfma_f32_32x32x16_bf16 v[76:91], v[36:39], v[132:135], v[76:91]
	v_mfma_f32_32x32x16_bf16 v[76:91], v[72:75], v[136:139], v[76:91]
	s_branch .Lm_ydone_17
.Lm_yfin1_14:
	ds_read_b64_tr_b16 v[36:37], v225 offset:0
	ds_read_b64_tr_b16 v[38:39], v225 offset:512
	ds_read_b64_tr_b16 v[72:73], v225 offset:1024
	ds_read_b64_tr_b16 v[74:75], v225 offset:1536
	s_waitcnt lgkmcnt(5)
	s_waitcnt lgkmcnt(4)
	ds_read_b128 v[148:151], v210 offset:0
	ds_read_b128 v[152:155], v210 offset:32
	ds_read_b128 v[156:159], v210 offset:64
	ds_read_b128 v[160:163], v210 offset:96
	s_waitcnt lgkmcnt(3)
	v_mfma_f32_32x32x16_bf16 v[92:107], v[148:151], v[176:179], 0
	ds_read_b128 v[148:151], v210 offset:128
	v_sub_f32_e32 v234, v250, v234
	v_sub_f32_e32 v235, v250, v235
	v_sub_f32_e32 v236, v250, v236
	v_sub_f32_e32 v237, v250, v237
	v_sub_f32_e32 v238, v250, v238
	v_sub_f32_e32 v239, v250, v239
	v_sub_f32_e32 v240, v250, v240
	v_sub_f32_e32 v241, v250, v241
	v_sub_f32_e32 v242, v250, v242
	s_waitcnt lgkmcnt(3)
	v_mfma_f32_32x32x16_bf16 v[92:107], v[152:155], v[180:183], v[92:107]
	ds_read_b128 v[152:155], v210 offset:160
	v_sub_f32_e32 v243, v250, v243
	v_sub_f32_e32 v244, v250, v244
	v_sub_f32_e32 v245, v250, v245
	v_sub_f32_e32 v246, v250, v246
	v_sub_f32_e32 v247, v250, v247
	v_sub_f32_e32 v248, v250, v248
	v_sub_f32_e32 v249, v250, v249
	v_exp_f32_e32 v234, v234
	v_exp_f32_e32 v235, v235
	s_waitcnt lgkmcnt(3)
	v_mfma_f32_32x32x16_bf16 v[92:107], v[156:159], v[184:187], v[92:107]
	ds_read_b128 v[156:159], v210 offset:192
	v_exp_f32_e32 v236, v236
	v_exp_f32_e32 v237, v237
	v_exp_f32_e32 v238, v238
	v_exp_f32_e32 v239, v239
	v_exp_f32_e32 v240, v240
	v_exp_f32_e32 v241, v241
	v_exp_f32_e32 v242, v242
	v_exp_f32_e32 v243, v243
	v_exp_f32_e32 v244, v244
	s_waitcnt lgkmcnt(3)
	v_mfma_f32_32x32x16_bf16 v[92:107], v[160:163], v[188:191], v[92:107]
	ds_read_b128 v[160:163], v210 offset:224
	v_exp_f32_e32 v245, v245
	v_exp_f32_e32 v246, v246
	v_exp_f32_e32 v247, v247
	v_exp_f32_e32 v248, v248
	v_exp_f32_e32 v249, v249
	v_mul_f32_e32 v116, v116, v234
	v_mul_f32_e32 v117, v117, v235
	v_mul_f32_e32 v118, v118, v236
	v_mul_f32_e32 v119, v119, v237
	s_waitcnt lgkmcnt(3)
	v_mfma_f32_32x32x16_bf16 v[92:107], v[148:151], v[192:195], v[92:107]
	v_mul_f32_e32 v120, v120, v238
	v_mul_f32_e32 v121, v121, v239
	v_mul_f32_e32 v122, v122, v240
	v_mul_f32_e32 v123, v123, v241
	v_mul_f32_e32 v124, v124, v242
	v_mul_f32_e32 v125, v125, v243
	v_mul_f32_e32 v126, v126, v244
	v_mul_f32_e32 v127, v127, v245
	v_mul_f32_e32 v128, v128, v246
	s_waitcnt lgkmcnt(2)
	v_mfma_f32_32x32x16_bf16 v[92:107], v[152:155], v[196:199], v[92:107]
	v_mul_f32_e32 v129, v129, v247
	v_mul_f32_e32 v130, v130, v248
	v_mul_f32_e32 v131, v131, v249
	v_cndmask_b32_e64 v116, 0, v116, s[64:65]
	v_cndmask_b32_e64 v117, 0, v117, s[66:67]
	v_cndmask_b32_e64 v118, 0, v118, s[68:69]
	v_cndmask_b32_e64 v119, 0, v119, s[70:71]
	v_cndmask_b32_e64 v120, 0, v120, s[72:73]
	v_cndmask_b32_e64 v121, 0, v121, s[74:75]
	s_waitcnt lgkmcnt(1)
	v_mfma_f32_32x32x16_bf16 v[92:107], v[156:159], v[200:203], v[92:107]
	v_cndmask_b32_e64 v122, 0, v122, s[76:77]
	v_cndmask_b32_e64 v123, 0, v123, s[78:79]
	v_cndmask_b32_e64 v124, 0, v124, s[80:81]
	v_cndmask_b32_e64 v125, 0, v125, s[82:83]
	v_cndmask_b32_e64 v126, 0, v126, s[84:85]
	v_cndmask_b32_e64 v127, 0, v127, s[86:87]
	v_cndmask_b32_e64 v128, 0, v128, s[88:89]
	v_cndmask_b32_e64 v129, 0, v129, s[90:91]
	v_cndmask_b32_e64 v130, 0, v130, s[92:93]
	s_waitcnt lgkmcnt(0)
	v_mfma_f32_32x32x16_bf16 v[92:107], v[160:163], v[204:207], v[92:107]
	v_cndmask_b32_e64 v131, 0, v131, s[94:95]
	v_cvt_pk_bf16_f32 v116, v116, v117
	v_cvt_pk_bf16_f32 v117, v118, v119
	v_cvt_pk_bf16_f32 v118, v120, v121
	v_cvt_pk_bf16_f32 v119, v122, v123
	v_cvt_pk_bf16_f32 v120, v124, v125
	v_cvt_pk_bf16_f32 v121, v126, v127
	v_cvt_pk_bf16_f32 v122, v128, v129
	v_cvt_pk_bf16_f32 v123, v130, v131
	v_mfma_f32_32x32x16_bf16 v[76:91], v[36:39], v[116:119], 0
	v_mfma_f32_32x32x16_bf16 v[76:91], v[72:75], v[120:123], v[76:91]
	s_branch .Lm_ydone_17
.Lm_yfin2_15:
	ds_read_b64_tr_b16 v[36:37], v225 offset:0
	ds_read_b64_tr_b16 v[38:39], v225 offset:512
	ds_read_b64_tr_b16 v[72:73], v225 offset:1024
	ds_read_b64_tr_b16 v[74:75], v225 offset:1536
	s_waitcnt lgkmcnt(4)
	ds_read_b128 v[148:151], v210 offset:0
	ds_read_b128 v[152:155], v210 offset:32
	ds_read_b128 v[156:159], v210 offset:64
	ds_read_b128 v[160:163], v210 offset:96
	s_waitcnt lgkmcnt(3)
	v_mfma_f32_32x32x16_bf16 v[92:107], v[148:151], v[176:179], 0
	ds_read_b128 v[148:151], v210 offset:128
	v_sub_f32_e32 v234, v250, v234
	v_sub_f32_e32 v235, v250, v235
	v_sub_f32_e32 v236, v250, v236
	v_sub_f32_e32 v237, v250, v237
	v_sub_f32_e32 v238, v250, v238
	v_sub_f32_e32 v239, v250, v239
	v_sub_f32_e32 v240, v250, v240
	s_waitcnt lgkmcnt(3)
	v_mfma_f32_32x32x16_bf16 v[92:107], v[152:155], v[180:183], v[92:107]
	ds_read_b128 v[152:155], v210 offset:160
	v_sub_f32_e32 v241, v250, v241
	v_sub_f32_e32 v242, v250, v242
	v_sub_f32_e32 v243, v250, v243
	v_sub_f32_e32 v244, v250, v244
	v_sub_f32_e32 v245, v250, v245
	v_sub_f32_e32 v246, v250, v246
	v_sub_f32_e32 v247, v250, v247
	s_waitcnt lgkmcnt(3)
	v_mfma_f32_32x32x16_bf16 v[92:107], v[156:159], v[184:187], v[92:107]
	ds_read_b128 v[156:159], v210 offset:192
	v_sub_f32_e32 v248, v250, v248
	v_sub_f32_e32 v249, v250, v249
	v_exp_f32_e32 v234, v234
	v_exp_f32_e32 v235, v235
	v_exp_f32_e32 v236, v236
	v_exp_f32_e32 v237, v237
	v_exp_f32_e32 v238, v238
	s_waitcnt lgkmcnt(3)
	v_mfma_f32_32x32x16_bf16 v[92:107], v[160:163], v[188:191], v[92:107]
	ds_read_b128 v[160:163], v210 offset:224
	v_exp_f32_e32 v239, v239
	v_exp_f32_e32 v240, v240
	v_exp_f32_e32 v241, v241
	v_exp_f32_e32 v242, v242
	v_exp_f32_e32 v243, v243
	v_exp_f32_e32 v244, v244
	v_exp_f32_e32 v245, v245
	s_waitcnt lgkmcnt(3)
	v_mfma_f32_32x32x16_bf16 v[92:107], v[148:151], v[192:195], v[92:107]
	v_exp_f32_e32 v246, v246
	v_exp_f32_e32 v247, v247
	v_exp_f32_e32 v248, v248
	v_exp_f32_e32 v249, v249
	v_mul_f32_e32 v132, v132, v234
	v_mul_f32_e32 v133, v133, v235
	v_mul_f32_e32 v134, v134, v236
	s_waitcnt lgkmcnt(2)
	v_mfma_f32_32x32x16_bf16 v[92:107], v[152:155], v[196:199], v[92:107]
	v_mul_f32_e32 v135, v135, v237
	v_mul_f32_e32 v136, v136, v238
	v_mul_f32_e32 v137, v137, v239
	v_mul_f32_e32 v138, v138, v240
	v_mul_f32_e32 v139, v139, v241
	v_mul_f32_e32 v140, v140, v242
	v_mul_f32_e32 v141, v141, v243
	s_waitcnt lgkmcnt(1)
	v_mfma_f32_32x32x16_bf16 v[92:107], v[156:159], v[200:203], v[92:107]
	v_mul_f32_e32 v142, v142, v244
	v_mul_f32_e32 v143, v143, v245
	v_mul_f32_e32 v144, v144, v246
	v_mul_f32_e32 v145, v145, v247
	v_mul_f32_e32 v146, v146, v248
	v_mul_f32_e32 v147, v147, v249
	v_cvt_pk_bf16_f32 v132, v132, v133
	s_waitcnt lgkmcnt(0)
	v_mfma_f32_32x32x16_bf16 v[92:107], v[160:163], v[204:207], v[92:107]
	v_cvt_pk_bf16_f32 v133, v134, v135
	v_cvt_pk_bf16_f32 v134, v136, v137
	v_cvt_pk_bf16_f32 v135, v138, v139
	v_cvt_pk_bf16_f32 v136, v140, v141
	v_cvt_pk_bf16_f32 v137, v142, v143
	v_cvt_pk_bf16_f32 v138, v144, v145
	v_cvt_pk_bf16_f32 v139, v146, v147
	v_mfma_f32_32x32x16_bf16 v[76:91], v[36:39], v[132:135], v[76:91]
	v_mfma_f32_32x32x16_bf16 v[76:91], v[72:75], v[136:139], v[76:91]
	s_branch .Lm_ydone_17
.Lm_yfin3_16:
	ds_read_b64_tr_b16 v[36:37], v225 offset:0
	ds_read_b64_tr_b16 v[38:39], v225 offset:512
	ds_read_b64_tr_b16 v[72:73], v225 offset:1024
	ds_read_b64_tr_b16 v[74:75], v225 offset:1536
	s_waitcnt lgkmcnt(4)
	ds_read_b128 v[148:151], v210 offset:0
	ds_read_b128 v[152:155], v210 offset:32
	ds_read_b128 v[156:159], v210 offset:64
	ds_read_b128 v[160:163], v210 offset:96
	s_waitcnt lgkmcnt(3)
	v_mfma_f32_32x32x16_bf16 v[92:107], v[148:151], v[176:179], 0
	ds_read_b128 v[148:151], v210 offset:128
	v_sub_f32_e32 v234, v250, v234
	v_sub_f32_e32 v235, v250, v235
	v_sub_f32_e32 v236, v250, v236
	v_sub_f32_e32 v237, v250, v237
	v_sub_f32_e32 v238, v250, v238
	v_sub_f32_e32 v239, v250, v239
	v_sub_f32_e32 v240, v250, v240
	s_waitcnt lgkmcnt(3)
	v_mfma_f32_32x32x16_bf16 v[92:107], v[152:155], v[180:183], v[92:107]
	ds_read_b128 v[152:155], v210 offset:160
	v_sub_f32_e32 v241, v250, v241
	v_sub_f32_e32 v242, v250, v242
	v_sub_f32_e32 v243, v250, v243
	v_sub_f32_e32 v244, v250, v244
	v_sub_f32_e32 v245, v250, v245
	v_sub_f32_e32 v246, v250, v246
	v_sub_f32_e32 v247, v250, v247
	s_waitcnt lgkmcnt(3)
	v_mfma_f32_32x32x16_bf16 v[92:107], v[156:159], v[184:187], v[92:107]
	ds_read_b128 v[156:159], v210 offset:192
	v_sub_f32_e32 v248, v250, v248
	v_sub_f32_e32 v249, v250, v249
	v_exp_f32_e32 v234, v234
	v_exp_f32_e32 v235, v235
	v_exp_f32_e32 v236, v236
	v_exp_f32_e32 v237, v237
	v_exp_f32_e32 v238, v238
	s_waitcnt lgkmcnt(3)
	v_mfma_f32_32x32x16_bf16 v[92:107], v[160:163], v[188:191], v[92:107]
	ds_read_b128 v[160:163], v210 offset:224
	v_exp_f32_e32 v239, v239
	v_exp_f32_e32 v240, v240
	v_exp_f32_e32 v241, v241
	v_exp_f32_e32 v242, v242
	v_exp_f32_e32 v243, v243
	v_exp_f32_e32 v244, v244
	v_exp_f32_e32 v245, v245
	s_waitcnt lgkmcnt(3)
	v_mfma_f32_32x32x16_bf16 v[92:107], v[148:151], v[192:195], v[92:107]
	v_exp_f32_e32 v246, v246
	v_exp_f32_e32 v247, v247
	v_exp_f32_e32 v248, v248
	v_exp_f32_e32 v249, v249
	v_mul_f32_e32 v116, v116, v234
	v_mul_f32_e32 v117, v117, v235
	v_mul_f32_e32 v118, v118, v236
	s_waitcnt lgkmcnt(2)
	v_mfma_f32_32x32x16_bf16 v[92:107], v[152:155], v[196:199], v[92:107]
	v_mul_f32_e32 v119, v119, v237
	v_mul_f32_e32 v120, v120, v238
	v_mul_f32_e32 v121, v121, v239
	v_mul_f32_e32 v122, v122, v240
	v_mul_f32_e32 v123, v123, v241
	v_mul_f32_e32 v124, v124, v242
	v_mul_f32_e32 v125, v125, v243
	s_waitcnt lgkmcnt(1)
	v_mfma_f32_32x32x16_bf16 v[92:107], v[156:159], v[200:203], v[92:107]
	v_mul_f32_e32 v126, v126, v244
	v_mul_f32_e32 v127, v127, v245
	v_mul_f32_e32 v128, v128, v246
	v_mul_f32_e32 v129, v129, v247
	v_mul_f32_e32 v130, v130, v248
	v_mul_f32_e32 v131, v131, v249
	v_cvt_pk_bf16_f32 v116, v116, v117
	s_waitcnt lgkmcnt(0)
	v_mfma_f32_32x32x16_bf16 v[92:107], v[160:163], v[204:207], v[92:107]
	v_cvt_pk_bf16_f32 v117, v118, v119
	v_cvt_pk_bf16_f32 v118, v120, v121
	v_cvt_pk_bf16_f32 v119, v122, v123
	v_cvt_pk_bf16_f32 v120, v124, v125
	v_cvt_pk_bf16_f32 v121, v126, v127
	v_cvt_pk_bf16_f32 v122, v128, v129
	v_cvt_pk_bf16_f32 v123, v130, v131
	v_mfma_f32_32x32x16_bf16 v[76:91], v[36:39], v[116:119], v[76:91]
	v_mfma_f32_32x32x16_bf16 v[76:91], v[72:75], v[120:123], v[76:91]

.Lm_hi_11:
	ds_read_b32 v1, v172 offset:0
	ds_read_b64_tr_b16 v[116:117], v193 offset:0
	ds_read_b64_tr_b16 v[118:119], v193 offset:1088
	ds_read_b64_tr_b16 v[120:121], v192 offset:0
	ds_read_b64_tr_b16 v[122:123], v192 offset:256
	ds_read_b64_tr_b16 v[124:125], v193 offset:4352
	ds_read_b64_tr_b16 v[126:127], v193 offset:5440
	ds_read_b64_tr_b16 v[128:129], v192 offset:1024
	ds_read_b64_tr_b16 v[130:131], v192 offset:1280
	ds_read_b64_tr_b16 v[132:133], v193 offset:8704
	ds_read_b64_tr_b16 v[134:135], v193 offset:9792
	ds_read_b64_tr_b16 v[136:137], v192 offset:2048
	ds_read_b64_tr_b16 v[138:139], v192 offset:2304
	s_waitcnt lgkmcnt(12)
	v_exp_f32_e32 v1, v1
	s_nop 0
	v_mul_f32_e32 v176, v176, v1
	v_mul_f32_e32 v177, v177, v1
	v_mul_f32_e32 v178, v178, v1
	v_mul_f32_e32 v179, v179, v1
	v_mul_f32_e32 v180, v180, v1
	v_mul_f32_e32 v181, v181, v1
	v_mul_f32_e32 v182, v182, v1
	v_mul_f32_e32 v183, v183, v1
	v_mul_f32_e32 v184, v184, v1
	v_mul_f32_e32 v185, v185, v1
	v_mul_f32_e32 v186, v186, v1
	v_mul_f32_e32 v187, v187, v1
	v_mul_f32_e32 v188, v188, v1
	v_mul_f32_e32 v189, v189, v1
	v_mul_f32_e32 v190, v190, v1
	v_mul_f32_e32 v191, v191, v1
	s_nop 1
	s_waitcnt lgkmcnt(8)
	v_mfma_f32_32x32x16_bf16 v[176:191], v[116:119], v[120:123], v[176:191]
	ds_read_b64_tr_b16 v[116:117], v193 offset:13056
	ds_read_b64_tr_b16 v[118:119], v193 offset:14144
	ds_read_b64_tr_b16 v[120:121], v192 offset:3072
	ds_read_b64_tr_b16 v[122:123], v192 offset:3328
	global_load_dwordx4 v[4:7], v164, s[38:39]
	s_waitcnt lgkmcnt(8)
	v_mfma_f32_32x32x16_bf16 v[176:191], v[124:127], v[128:131], v[176:191]
	ds_read_b64_tr_b16 v[124:125], v193 offset:17408
	ds_read_b64_tr_b16 v[126:127], v193 offset:18496
	ds_read_b64_tr_b16 v[128:129], v192 offset:4096
	ds_read_b64_tr_b16 v[130:131], v192 offset:4352
	global_load_dwordx4 v[20:23], v164, s[38:39] offset:256
	s_waitcnt lgkmcnt(8)
	v_mfma_f32_32x32x16_bf16 v[176:191], v[132:135], v[136:139], v[176:191]
	ds_read_b64_tr_b16 v[132:133], v193 offset:21760
	ds_read_b64_tr_b16 v[134:135], v193 offset:22848
	ds_read_b64_tr_b16 v[136:137], v192 offset:5120
	ds_read_b64_tr_b16 v[138:139], v192 offset:5376
	global_load_dwordx4 v[8:11], v165, s[38:39]
	s_waitcnt lgkmcnt(8)
	v_mfma_f32_32x32x16_bf16 v[176:191], v[116:119], v[120:123], v[176:191]
	ds_read_b64_tr_b16 v[116:117], v193 offset:26112
	ds_read_b64_tr_b16 v[118:119], v193 offset:27200
	ds_read_b64_tr_b16 v[120:121], v192 offset:6144
	ds_read_b64_tr_b16 v[122:123], v192 offset:6400
	global_load_dwordx4 v[24:27], v165, s[38:39] offset:256
	s_waitcnt lgkmcnt(8)
	v_mfma_f32_32x32x16_bf16 v[176:191], v[124:127], v[128:131], v[176:191]
	ds_read_b64_tr_b16 v[124:125], v193 offset:30464
	ds_read_b64_tr_b16 v[126:127], v193 offset:31552
	ds_read_b64_tr_b16 v[128:129], v192 offset:7168
	ds_read_b64_tr_b16 v[130:131], v192 offset:7424
	global_load_dwordx4 v[12:15], v166, s[38:39]
	s_waitcnt lgkmcnt(8)
	v_mfma_f32_32x32x16_bf16 v[176:191], v[132:135], v[136:139], v[176:191]
	global_load_dwordx4 v[28:31], v166, s[38:39] offset:256
	s_waitcnt lgkmcnt(4)
	v_mfma_f32_32x32x16_bf16 v[176:191], v[116:119], v[120:123], v[176:191]
	global_load_dwordx4 v[16:19], v167, s[38:39]
	s_waitcnt lgkmcnt(0)
	v_mfma_f32_32x32x16_bf16 v[176:191], v[124:127], v[128:131], v[176:191]
	global_load_dwordx4 v[32:35], v167, s[38:39] offset:256
	global_load_dwordx4 v[36:39], v168, s[40:41]
	global_load_dwordx4 v[198:201], v202, s[40:41]
	s_add_u32 s38, s38, s46
	s_addc_u32 s39, s39, s55
	s_add_u32 s40, s40, s47
	s_addc_u32 s41, s41, s55
	s_nop 7
	s_nop 3
	v_cvt_pk_bf16_f32 v140, v176, v177
	v_cvt_pk_bf16_f32 v141, v178, v179
	v_cvt_pk_bf16_f32 v142, v180, v181
	v_cvt_pk_bf16_f32 v143, v182, v183
	v_cvt_pk_bf16_f32 v144, v184, v185
	v_cvt_pk_bf16_f32 v145, v186, v187
	v_cvt_pk_bf16_f32 v146, v188, v189
	v_cvt_pk_bf16_f32 v147, v190, v191
	ds_write_b64 v194, v[140:141] offset:8704
	ds_write_b64 v194, v[142:143] offset:8720
	ds_write_b64 v194, v[144:145] offset:8736
	ds_write_b64 v194, v[146:147] offset:8752
	s_cmp_eq_u32 s3, 7
	s_cbranch_scc0 .Lm_noscan_13
	s_cmp_lt_u32 s50, 63
	s_cbranch_scc0 .Lm_noscan_13
	s_waitcnt vmcnt(10)
	v_mul_f32_e32 v116, s62, v204
	v_mul_f32_e32 v117, s62, v205
	v_add_f32_e32 v118, v116, v117
	s_nop 1
	v_add_f32_dpp v118, v118, v118 row_shr:1 row_mask:0xf bank_mask:0xf bound_ctrl:0
	s_nop 1
	v_add_f32_dpp v118, v118, v118 row_shr:2 row_mask:0xf bank_mask:0xf bound_ctrl:0
	s_nop 1
	v_add_f32_dpp v118, v118, v118 row_shr:4 row_mask:0xf bank_mask:0xf bound_ctrl:0
	s_nop 1
	v_add_f32_dpp v118, v118, v118 row_shr:8 row_mask:0xf bank_mask:0xf bound_ctrl:0
	s_nop 1
	v_add_f32_dpp v118, v118, v118 row_bcast:15 row_mask:0xa bank_mask:0xf
	s_nop 1
	v_add_f32_dpp v118, v118, v118 row_bcast:31 row_mask:0xc bank_mask:0xf
	s_nop 1
	v_readlane_b32 s97, v118, 63
	v_sub_f32_e32 v122, v118, v117
	v_mov_b32_e32 v123, v118
	s_nop 1
	s_cmp_eq_u32 s51, 0
	s_cbranch_scc1 .Lm_scanf_18
	v_sub_f32_e32 v122, s97, v122
	v_sub_f32_e32 v123, s97, v123
	v_fma_f32 v122, v204, s62, v122
	v_fma_f32 v123, v205, s62, v123

.Lm_noscan_13:
.Lm_adone_12:
	s_waitcnt lgkmcnt(0)
	s_barrier
	s_cmp_lt_u32 s50, 63
	s_cbranch_scc0 .Lm_now_19
	s_cmp_lt_u32 s3, 4
	s_cbranch_scc0 .Lm_whi_23
	s_waitcnt vmcnt(8)
	ds_write_b128 v169, v[56:59] offset:0
	ds_write_b128 v169, v[40:43] offset:34816
	ds_write_b128 v169, v[60:63] offset:8704
	ds_write_b128 v169, v[44:47] offset:43520
	ds_write_b128 v169, v[64:67] offset:17408
	ds_write_b128 v169, v[48:51] offset:52224
	ds_write_b128 v169, v[68:71] offset:26112
	ds_write_b128 v169, v[52:55] offset:60928
	s_branch .Lm_now_19

.Lm_now_19:
	s_nop 7
	s_nop 3
	s_cmp_lt_u32 s3, 4
	s_cbranch_scc0 .Lm_noy2_20
	v_exp_f32_e32 v250, v250
	s_nop 0
	v_fma_f32 v76, v92, v250, v76
	v_fma_f32 v77, v93, v250, v77
	v_fma_f32 v78, v94, v250, v78
	v_fma_f32 v79, v95, v250, v79
	v_fma_f32 v80, v96, v250, v80
	v_fma_f32 v81, v97, v250, v81
	v_fma_f32 v82, v98, v250, v82
	v_fma_f32 v83, v99, v250, v83
	v_fma_f32 v84, v100, v250, v84
	v_fma_f32 v85, v101, v250, v85
	v_fma_f32 v86, v102, v250, v86
	v_fma_f32 v87, v103, v250, v87
	v_fma_f32 v88, v104, v250, v88
	v_fma_f32 v89, v105, v250, v89
	v_fma_f32 v90, v106, v250, v90
	v_fma_f32 v91, v107, v250, v91
	v_cvt_pk_bf16_f32 v156, v76, v77
	v_cvt_pk_bf16_f32 v157, v78, v79
	v_cvt_pk_bf16_f32 v158, v80, v81
	v_cvt_pk_bf16_f32 v159, v82, v83
	v_cvt_pk_bf16_f32 v160, v84, v85
	v_cvt_pk_bf16_f32 v161, v86, v87
	v_cvt_pk_bf16_f32 v162, v88, v89
	v_cvt_pk_bf16_f32 v163, v90, v91
	global_store_dwordx2 v212, v[156:157], s[44:45] offset:0
	global_store_dwordx2 v212, v[158:159], s[44:45] offset:16
	global_store_dwordx2 v212, v[160:161], s[44:45] offset:32
	global_store_dwordx2 v212, v[162:163], s[44:45] offset:48
.Lm_noy2_20:
	s_add_u32 s44, s44, s49
	s_addc_u32 s45, s45, s55
	s_waitcnt lgkmcnt(0)
	s_barrier
	s_add_u32 s50, s50, 1
	s_cmp_lt_u32 s3, 4
	s_cbranch_scc0 .Lm_hi_24
	v_mov_b32_e32 v223, v173
	v_mov_b32_e32 v224, v217
	v_mov_b32_e32 v225, v222
	ds_read_b128 v[176:179], v173 offset:0
	ds_read_b128 v[180:183], v173 offset:32
	ds_read_b128 v[184:187], v173 offset:64
	ds_read_b128 v[188:191], v173 offset:96
	ds_read_b128 v[192:195], v173 offset:128
	ds_read_b128 v[196:199], v173 offset:160
	ds_read_b128 v[200:203], v173 offset:192
	ds_read_b128 v[204:207], v173 offset:224
	ds_read_b128 v[148:151], v223 offset:34816
	ds_read_b128 v[152:155], v223 offset:34848
	ds_read_b128 v[156:159], v223 offset:34880
	ds_read_b128 v[160:163], v223 offset:34912
	s_waitcnt lgkmcnt(11)
	s_waitcnt lgkmcnt(3)
	v_mfma_f32_32x32x16_bf16 v[116:131], v[148:151], v[176:179], 0
	ds_read_b128 v[148:151], v223 offset:34944
	global_load_dwordx4 v[40:43], v164, s[38:39]
	s_waitcnt lgkmcnt(3)
	v_mfma_f32_32x32x16_bf16 v[116:131], v[152:155], v[180:183], v[116:131]
	ds_read_b128 v[152:155], v223 offset:34976
	global_load_dwordx4 v[56:59], v164, s[38:39] offset:256
	s_waitcnt lgkmcnt(3)
	v_mfma_f32_32x32x16_bf16 v[116:131], v[156:159], v[184:187], v[116:131]
	ds_read_b128 v[156:159], v223 offset:35008
	global_load_dwordx4 v[44:47], v165, s[38:39]
	s_waitcnt lgkmcnt(3)
	v_mfma_f32_32x32x16_bf16 v[116:131], v[160:163], v[188:191], v[116:131]
	ds_read_b128 v[160:163], v223 offset:35040
	global_load_dwordx4 v[60:63], v165, s[38:39] offset:256
	ds_read_b128 v[234:237], v224 offset:2048
	ds_read_b128 v[238:241], v224 offset:2080
	ds_read_b128 v[242:245], v224 offset:2112
	ds_read_b128 v[246:249], v224 offset:2144
	ds_read_b32 v250, v211 offset:2048
	s_waitcnt lgkmcnt(8)
	v_mfma_f32_32x32x16_bf16 v[116:131], v[148:151], v[192:195], v[116:131]
	global_load_dwordx4 v[48:51], v166, s[38:39]
	s_waitcnt lgkmcnt(7)
	v_mfma_f32_32x32x16_bf16 v[116:131], v[152:155], v[196:199], v[116:131]
	global_load_dwordx4 v[64:67], v166, s[38:39] offset:256
	s_waitcnt lgkmcnt(6)
	v_mfma_f32_32x32x16_bf16 v[116:131], v[156:159], v[200:203], v[116:131]
	global_load_dwordx4 v[52:55], v167, s[38:39]
	s_waitcnt lgkmcnt(5)
	v_mfma_f32_32x32x16_bf16 v[116:131], v[160:163], v[204:207], v[116:131]
	global_load_dwordx4 v[68:71], v167, s[38:39] offset:256
	s_add_u32 s38, s38, s46
	s_addc_u32 s39, s39, s55
	s_add_u32 s40, s40, s47
	s_addc_u32 s41, s41, s55
	s_cmp_eq_u32 s52, 1
	s_cbranch_scc1 .Lm_yfin1_27
	ds_read_b64_tr_b16 v[36:37], v225 offset:43008
	ds_read_b64_tr_b16 v[38:39], v225 offset:43520
	ds_read_b64_tr_b16 v[72:73], v225 offset:44032
	ds_read_b64_tr_b16 v[74:75], v225 offset:44544
	v_add_u32_e32 v223, s53, v223
	v_add_u32_e32 v224, s54, v224
	v_add_u32_e32 v225, s13, v225
	ds_read_b128 v[148:151], v223 offset:34816
	ds_read_b128 v[152:155], v223 offset:34848
	ds_read_b128 v[156:159], v223 offset:34880
	ds_read_b128 v[160:163], v223 offset:34912
	s_waitcnt lgkmcnt(9)
	s_waitcnt lgkmcnt(8)
	s_waitcnt lgkmcnt(3)
	v_mfma_f32_32x32x16_bf16 v[132:147], v[148:151], v[176:179], 0
	ds_read_b128 v[148:151], v223 offset:34944
	v_sub_f32_e32 v234, v250, v234
	v_sub_f32_e32 v235, v250, v235
	v_sub_f32_e32 v236, v250, v236
	v_sub_f32_e32 v237, v250, v237
	v_sub_f32_e32 v238, v250, v238
	v_sub_f32_e32 v239, v250, v239
	v_sub_f32_e32 v240, v250, v240
	v_sub_f32_e32 v241, v250, v241
	v_sub_f32_e32 v242, v250, v242
	s_waitcnt lgkmcnt(3)
	v_mfma_f32_32x32x16_bf16 v[132:147], v[152:155], v[180:183], v[132:147]
	ds_read_b128 v[152:155], v223 offset:34976
	v_sub_f32_e32 v243, v250, v243
	v_sub_f32_e32 v244, v250, v244
	v_sub_f32_e32 v245, v250, v245
	v_sub_f32_e32 v246, v250, v246
	v_sub_f32_e32 v247, v250, v247
	v_sub_f32_e32 v248, v250, v248
	v_sub_f32_e32 v249, v250, v249
	v_exp_f32_e32 v234, v234
	v_exp_f32_e32 v235, v235
	s_waitcnt lgkmcnt(3)
	v_mfma_f32_32x32x16_bf16 v[132:147], v[156:159], v[184:187], v[132:147]
	ds_read_b128 v[156:159], v223 offset:35008
	v_exp_f32_e32 v236, v236
	v_exp_f32_e32 v237, v237
	v_exp_f32_e32 v238, v238
	v_exp_f32_e32 v239, v239
	v_exp_f32_e32 v240, v240
	v_exp_f32_e32 v241, v241
	v_exp_f32_e32 v242, v242
	v_exp_f32_e32 v243, v243
	v_exp_f32_e32 v244, v244
	s_waitcnt lgkmcnt(3)
	v_mfma_f32_32x32x16_bf16 v[132:147], v[160:163], v[188:191], v[132:147]
	ds_read_b128 v[160:163], v223 offset:35040
	v_exp_f32_e32 v245, v245
	v_exp_f32_e32 v246, v246
	v_exp_f32_e32 v247, v247
	v_exp_f32_e32 v248, v248
	v_exp_f32_e32 v249, v249
	v_mul_f32_e32 v116, v116, v234
	v_mul_f32_e32 v117, v117, v235
	v_mul_f32_e32 v118, v118, v236
	v_mul_f32_e32 v119, v119, v237
	s_waitcnt lgkmcnt(3)
	v_mfma_f32_32x32x16_bf16 v[132:147], v[148:151], v[192:195], v[132:147]
	v_mul_f32_e32 v120, v120, v238
	v_mul_f32_e32 v121, v121, v239
	v_mul_f32_e32 v122, v122, v240
	v_mul_f32_e32 v123, v123, v241
	v_mul_f32_e32 v124, v124, v242
	v_mul_f32_e32 v125, v125, v243
	v_mul_f32_e32 v126, v126, v244
	v_mul_f32_e32 v127, v127, v245
	v_mul_f32_e32 v128, v128, v246
	s_waitcnt lgkmcnt(2)
	v_mfma_f32_32x32x16_bf16 v[132:147], v[152:155], v[196:199], v[132:147]
	v_mul_f32_e32 v129, v129, v247
	v_mul_f32_e32 v130, v130, v248
	v_mul_f32_e32 v131, v131, v249
	v_cndmask_b32_e64 v116, 0, v116, s[64:65]
	v_cndmask_b32_e64 v117, 0, v117, s[66:67]
	v_cndmask_b32_e64 v118, 0, v118, s[68:69]
	v_cndmask_b32_e64 v119, 0, v119, s[70:71]
	v_cndmask_b32_e64 v120, 0, v120, s[72:73]
	v_cndmask_b32_e64 v121, 0, v121, s[74:75]
	s_waitcnt lgkmcnt(1)
	v_mfma_f32_32x32x16_bf16 v[132:147], v[156:159], v[200:203], v[132:147]
	v_cndmask_b32_e64 v122, 0, v122, s[76:77]
	v_cndmask_b32_e64 v123, 0, v123, s[78:79]
	v_cndmask_b32_e64 v124, 0, v124, s[80:81]
	v_cndmask_b32_e64 v125, 0, v125, s[82:83]
	v_cndmask_b32_e64 v126, 0, v126, s[84:85]
	v_cndmask_b32_e64 v127, 0, v127, s[86:87]
	v_cndmask_b32_e64 v128, 0, v128, s[88:89]
	v_cndmask_b32_e64 v129, 0, v129, s[90:91]
	v_cndmask_b32_e64 v130, 0, v130, s[92:93]
	s_waitcnt lgkmcnt(0)
	v_mfma_f32_32x32x16_bf16 v[132:147], v[160:163], v[204:207], v[132:147]
	v_cndmask_b32_e64 v131, 0, v131, s[94:95]
	v_cvt_pk_bf16_f32 v116, v116, v117
	v_cvt_pk_bf16_f32 v117, v118, v119
	v_cvt_pk_bf16_f32 v118, v120, v121
	v_cvt_pk_bf16_f32 v119, v122, v123
	v_cvt_pk_bf16_f32 v120, v124, v125
	v_cvt_pk_bf16_f32 v121, v126, v127
	v_cvt_pk_bf16_f32 v122, v128, v129
	v_cvt_pk_bf16_f32 v123, v130, v131
	ds_read_b128 v[234:237], v224 offset:2048
	ds_read_b128 v[238:241], v224 offset:2080
	ds_read_b128 v[242:245], v224 offset:2112
	ds_read_b128 v[246:249], v224 offset:2144
	v_mfma_f32_32x32x16_bf16 v[76:91], v[36:39], v[116:119], 0
	v_mfma_f32_32x32x16_bf16 v[76:91], v[72:75], v[120:123], v[76:91]
	s_cmp_eq_u32 s52, 2
	s_cbranch_scc1 .Lm_yfin2_28
	ds_read_b64_tr_b16 v[36:37], v225 offset:43008
	ds_read_b64_tr_b16 v[38:39], v225 offset:43520
	ds_read_b64_tr_b16 v[72:73], v225 offset:44032
	ds_read_b64_tr_b16 v[74:75], v225 offset:44544
	v_add_u32_e32 v223, s53, v223
	v_add_u32_e32 v224, s54, v224
	v_add_u32_e32 v225, s13, v225
	ds_read_b128 v[148:151], v223 offset:34816
	ds_read_b128 v[152:155], v223 offset:34848
	ds_read_b128 v[156:159], v223 offset:34880
	ds_read_b128 v[160:163], v223 offset:34912
	s_waitcnt lgkmcnt(8)
	s_waitcnt lgkmcnt(3)
	v_mfma_f32_32x32x16_bf16 v[116:131], v[148:151], v[176:179], 0
	ds_read_b128 v[148:151], v223 offset:34944
	v_sub_f32_e32 v234, v250, v234
	v_sub_f32_e32 v235, v250, v235
	v_sub_f32_e32 v236, v250, v236
	v_sub_f32_e32 v237, v250, v237
	v_sub_f32_e32 v238, v250, v238
	v_sub_f32_e32 v239, v250, v239
	v_sub_f32_e32 v240, v250, v240
	s_waitcnt lgkmcnt(3)
	v_mfma_f32_32x32x16_bf16 v[116:131], v[152:155], v[180:183], v[116:131]
	ds_read_b128 v[152:155], v223 offset:34976
	v_sub_f32_e32 v241, v250, v241
	v_sub_f32_e32 v242, v250, v242
	v_sub_f32_e32 v243, v250, v243
	v_sub_f32_e32 v244, v250, v244
	v_sub_f32_e32 v245, v250, v245
	v_sub_f32_e32 v246, v250, v246
	v_sub_f32_e32 v247, v250, v247
	s_waitcnt lgkmcnt(3)
	v_mfma_f32_32x32x16_bf16 v[116:131], v[156:159], v[184:187], v[116:131]
	ds_read_b128 v[156:159], v223 offset:35008
	v_sub_f32_e32 v248, v250, v248
	v_sub_f32_e32 v249, v250, v249
	v_exp_f32_e32 v234, v234
	v_exp_f32_e32 v235, v235
	v_exp_f32_e32 v236, v236
	v_exp_f32_e32 v237, v237
	v_exp_f32_e32 v238, v238
	s_waitcnt lgkmcnt(3)
	v_mfma_f32_32x32x16_bf16 v[116:131], v[160:163], v[188:191], v[116:131]
	ds_read_b128 v[160:163], v223 offset:35040
	v_exp_f32_e32 v239, v239
	v_exp_f32_e32 v240, v240
	v_exp_f32_e32 v241, v241
	v_exp_f32_e32 v242, v242
	v_exp_f32_e32 v243, v243
	v_exp_f32_e32 v244, v244
	v_exp_f32_e32 v245, v245
	s_waitcnt lgkmcnt(3)
	v_mfma_f32_32x32x16_bf16 v[116:131], v[148:151], v[192:195], v[116:131]
	v_exp_f32_e32 v246, v246
	v_exp_f32_e32 v247, v247
	v_exp_f32_e32 v248, v248
	v_exp_f32_e32 v249, v249
	v_mul_f32_e32 v132, v132, v234
	v_mul_f32_e32 v133, v133, v235
	v_mul_f32_e32 v134, v134, v236
	s_waitcnt lgkmcnt(2)
	v_mfma_f32_32x32x16_bf16 v[116:131], v[152:155], v[196:199], v[116:131]
	v_mul_f32_e32 v135, v135, v237
	v_mul_f32_e32 v136, v136, v238
	v_mul_f32_e32 v137, v137, v239
	v_mul_f32_e32 v138, v138, v240
	v_mul_f32_e32 v139, v139, v241
	v_mul_f32_e32 v140, v140, v242
	v_mul_f32_e32 v141, v141, v243
	s_waitcnt lgkmcnt(1)
	v_mfma_f32_32x32x16_bf16 v[116:131], v[156:159], v[200:203], v[116:131]
	v_mul_f32_e32 v142, v142, v244
	v_mul_f32_e32 v143, v143, v245
	v_mul_f32_e32 v144, v144, v246
	v_mul_f32_e32 v145, v145, v247
	v_mul_f32_e32 v146, v146, v248
	v_mul_f32_e32 v147, v147, v249
	v_cvt_pk_bf16_f32 v132, v132, v133
	s_waitcnt lgkmcnt(0)
	v_mfma_f32_32x32x16_bf16 v[116:131], v[160:163], v[204:207], v[116:131]
	v_cvt_pk_bf16_f32 v133, v134, v135
	v_cvt_pk_bf16_f32 v134, v136, v137
	v_cvt_pk_bf16_f32 v135, v138, v139
	v_cvt_pk_bf16_f32 v136, v140, v141
	v_cvt_pk_bf16_f32 v137, v142, v143
	v_cvt_pk_bf16_f32 v138, v144, v145
	v_cvt_pk_bf16_f32 v139, v146, v147
	ds_read_b128 v[234:237], v224 offset:2048
	ds_read_b128 v[238:241], v224 offset:2080
	ds_read_b128 v[242:245], v224 offset:2112
	ds_read_b128 v[246:249], v224 offset:2144
	v_mfma_f32_32x32x16_bf16 v[76:91], v[36:39], v[132:135], v[76:91]
	v_mfma_f32_32x32x16_bf16 v[76:91], v[72:75], v[136:139], v[76:91]
	s_cmp_eq_u32 s52, 3
	s_cbranch_scc1 .Lm_yfin3_29
	ds_read_b64_tr_b16 v[36:37], v225 offset:43008
	ds_read_b64_tr_b16 v[38:39], v225 offset:43520
	ds_read_b64_tr_b16 v[72:73], v225 offset:44032
	ds_read_b64_tr_b16 v[74:75], v225 offset:44544
	v_add_u32_e32 v223, s53, v223
	v_add_u32_e32 v224, s54, v224
	v_add_u32_e32 v225, s13, v225
	ds_read_b128 v[148:151], v223 offset:34816
	ds_read_b128 v[152:155], v223 offset:34848
	ds_read_b128 v[156:159], v223 offset:34880
	ds_read_b128 v[160:163], v223 offset:34912
	s_waitcnt lgkmcnt(8)
	s_waitcnt lgkmcnt(3)
	v_mfma_f32_32x32x16_bf16 v[132:147], v[148:151], v[176:179], 0
	ds_read_b128 v[148:151], v223 offset:34944
	v_sub_f32_e32 v234, v250, v234
	v_sub_f32_e32 v235, v250, v235
	v_sub_f32_e32 v236, v250, v236
	v_sub_f32_e32 v237, v250, v237
	v_sub_f32_e32 v238, v250, v238
	v_sub_f32_e32 v239, v250, v239
	v_sub_f32_e32 v240, v250, v240
	s_waitcnt lgkmcnt(3)
	v_mfma_f32_32x32x16_bf16 v[132:147], v[152:155], v[180:183], v[132:147]
	ds_read_b128 v[152:155], v223 offset:34976
	v_sub_f32_e32 v241, v250, v241
	v_sub_f32_e32 v242, v250, v242
	v_sub_f32_e32 v243, v250, v243
	v_sub_f32_e32 v244, v250, v244
	v_sub_f32_e32 v245, v250, v245
	v_sub_f32_e32 v246, v250, v246
	v_sub_f32_e32 v247, v250, v247
	s_waitcnt lgkmcnt(3)
	v_mfma_f32_32x32x16_bf16 v[132:147], v[156:159], v[184:187], v[132:147]
	ds_read_b128 v[156:159], v223 offset:35008
	v_sub_f32_e32 v248, v250, v248
	v_sub_f32_e32 v249, v250, v249
	v_exp_f32_e32 v234, v234
	v_exp_f32_e32 v235, v235
	v_exp_f32_e32 v236, v236
	v_exp_f32_e32 v237, v237
	v_exp_f32_e32 v238, v238
	s_waitcnt lgkmcnt(3)
	v_mfma_f32_32x32x16_bf16 v[132:147], v[160:163], v[188:191], v[132:147]
	ds_read_b128 v[160:163], v223 offset:35040
	v_exp_f32_e32 v239, v239
	v_exp_f32_e32 v240, v240
	v_exp_f32_e32 v241, v241
	v_exp_f32_e32 v242, v242
	v_exp_f32_e32 v243, v243
	v_exp_f32_e32 v244, v244
	v_exp_f32_e32 v245, v245
	s_waitcnt lgkmcnt(3)
	v_mfma_f32_32x32x16_bf16 v[132:147], v[148:151], v[192:195], v[132:147]
	v_exp_f32_e32 v246, v246
	v_exp_f32_e32 v247, v247
	v_exp_f32_e32 v248, v248
	v_exp_f32_e32 v249, v249
	v_mul_f32_e32 v116, v116, v234
	v_mul_f32_e32 v117, v117, v235
	v_mul_f32_e32 v118, v118, v236
	s_waitcnt lgkmcnt(2)
	v_mfma_f32_32x32x16_bf16 v[132:147], v[152:155], v[196:199], v[132:147]
	v_mul_f32_e32 v119, v119, v237
	v_mul_f32_e32 v120, v120, v238
	v_mul_f32_e32 v121, v121, v239
	v_mul_f32_e32 v122, v122, v240
	v_mul_f32_e32 v123, v123, v241
	v_mul_f32_e32 v124, v124, v242
	v_mul_f32_e32 v125, v125, v243
	s_waitcnt lgkmcnt(1)
	v_mfma_f32_32x32x16_bf16 v[132:147], v[156:159], v[200:203], v[132:147]
	v_mul_f32_e32 v126, v126, v244
	v_mul_f32_e32 v127, v127, v245
	v_mul_f32_e32 v128, v128, v246
	v_mul_f32_e32 v129, v129, v247
	v_mul_f32_e32 v130, v130, v248
	v_mul_f32_e32 v131, v131, v249
	v_cvt_pk_bf16_f32 v116, v116, v117
	s_waitcnt lgkmcnt(0)
	v_mfma_f32_32x32x16_bf16 v[132:147], v[160:163], v[204:207], v[132:147]
	v_cvt_pk_bf16_f32 v117, v118, v119
	v_cvt_pk_bf16_f32 v118, v120, v121
	v_cvt_pk_bf16_f32 v119, v122, v123
	v_cvt_pk_bf16_f32 v120, v124, v125
	v_cvt_pk_bf16_f32 v121, v126, v127
	v_cvt_pk_bf16_f32 v122, v128, v129
	v_cvt_pk_bf16_f32 v123, v130, v131
	ds_read_b128 v[234:237], v224 offset:2048
	ds_read_b128 v[238:241], v224 offset:2080
	ds_read_b128 v[242:245], v224 offset:2112
	ds_read_b128 v[246:249], v224 offset:2144
	v_mfma_f32_32x32x16_bf16 v[76:91], v[36:39], v[116:119], v[76:91]
	v_mfma_f32_32x32x16_bf16 v[76:91], v[72:75], v[120:123], v[76:91]
	ds_read_b64_tr_b16 v[36:37], v225 offset:43008
	ds_read_b64_tr_b16 v[38:39], v225 offset:43520
	ds_read_b64_tr_b16 v[72:73], v225 offset:44032
	ds_read_b64_tr_b16 v[74:75], v225 offset:44544
	s_waitcnt lgkmcnt(4)
	ds_read_b128 v[148:151], v210 offset:8704
	ds_read_b128 v[152:155], v210 offset:8736
	ds_read_b128 v[156:159], v210 offset:8768
	ds_read_b128 v[160:163], v210 offset:8800
	s_waitcnt lgkmcnt(3)
	v_mfma_f32_32x32x16_bf16 v[92:107], v[148:151], v[176:179], 0
	ds_read_b128 v[148:151], v210 offset:8832
	v_sub_f32_e32 v234, v250, v234
	v_sub_f32_e32 v235, v250, v235
	v_sub_f32_e32 v236, v250, v236
	v_sub_f32_e32 v237, v250, v237
	v_sub_f32_e32 v238, v250, v238
	v_sub_f32_e32 v239, v250, v239
	v_sub_f32_e32 v240, v250, v240
	s_waitcnt lgkmcnt(3)
	v_mfma_f32_32x32x16_bf16 v[92:107], v[152:155], v[180:183], v[92:107]
	ds_read_b128 v[152:155], v210 offset:8864
	v_sub_f32_e32 v241, v250, v241
	v_sub_f32_e32 v242, v250, v242
	v_sub_f32_e32 v243, v250, v243
	v_sub_f32_e32 v244, v250, v244
	v_sub_f32_e32 v245, v250, v245
	v_sub_f32_e32 v246, v250, v246
	v_sub_f32_e32 v247, v250, v247
	s_waitcnt lgkmcnt(3)
	v_mfma_f32_32x32x16_bf16 v[92:107], v[156:159], v[184:187], v[92:107]
	ds_read_b128 v[156:159], v210 offset:8896
	v_sub_f32_e32 v248, v250, v248
	v_sub_f32_e32 v249, v250, v249
	v_exp_f32_e32 v234, v234
	v_exp_f32_e32 v235, v235
	v_exp_f32_e32 v236, v236
	v_exp_f32_e32 v237, v237
	v_exp_f32_e32 v238, v238
	s_waitcnt lgkmcnt(3)
	v_mfma_f32_32x32x16_bf16 v[92:107], v[160:163], v[188:191], v[92:107]
	ds_read_b128 v[160:163], v210 offset:8928
	v_exp_f32_e32 v239, v239
	v_exp_f32_e32 v240, v240
	v_exp_f32_e32 v241, v241
	v_exp_f32_e32 v242, v242
	v_exp_f32_e32 v243, v243
	v_exp_f32_e32 v244, v244
	v_exp_f32_e32 v245, v245
	s_waitcnt lgkmcnt(3)
	v_mfma_f32_32x32x16_bf16 v[92:107], v[148:151], v[192:195], v[92:107]
	v_exp_f32_e32 v246, v246
	v_exp_f32_e32 v247, v247
	v_exp_f32_e32 v248, v248
	v_exp_f32_e32 v249, v249
	v_mul_f32_e32 v132, v132, v234
	v_mul_f32_e32 v133, v133, v235
	v_mul_f32_e32 v134, v134, v236
	s_waitcnt lgkmcnt(2)
	v_mfma_f32_32x32x16_bf16 v[92:107], v[152:155], v[196:199], v[92:107]
	v_mul_f32_e32 v135, v135, v237
	v_mul_f32_e32 v136, v136, v238
	v_mul_f32_e32 v137, v137, v239
	v_mul_f32_e32 v138, v138, v240
	v_mul_f32_e32 v139, v139, v241
	v_mul_f32_e32 v140, v140, v242
	v_mul_f32_e32 v141, v141, v243
	s_waitcnt lgkmcnt(1)
	v_mfma_f32_32x32x16_bf16 v[92:107], v[156:159], v[200:203], v[92:107]
	v_mul_f32_e32 v142, v142, v244
	v_mul_f32_e32 v143, v143, v245
	v_mul_f32_e32 v144, v144, v246
	v_mul_f32_e32 v145, v145, v247
	v_mul_f32_e32 v146, v146, v248
	v_mul_f32_e32 v147, v147, v249
	v_cvt_pk_bf16_f32 v132, v132, v133
	s_waitcnt lgkmcnt(0)
	v_mfma_f32_32x32x16_bf16 v[92:107], v[160:163], v[204:207], v[92:107]
	v_cvt_pk_bf16_f32 v133, v134, v135
	v_cvt_pk_bf16_f32 v134, v136, v137
	v_cvt_pk_bf16_f32 v135, v138, v139
	v_cvt_pk_bf16_f32 v136, v140, v141
	v_cvt_pk_bf16_f32 v137, v142, v143
	v_cvt_pk_bf16_f32 v138, v144, v145
	v_cvt_pk_bf16_f32 v139, v146, v147
	v_mfma_f32_32x32x16_bf16 v[76:91], v[36:39], v[132:135], v[76:91]
	v_mfma_f32_32x32x16_bf16 v[76:91], v[72:75], v[136:139], v[76:91]
	s_branch .Lm_ydone_30
.Lm_yfin1_27:
	ds_read_b64_tr_b16 v[36:37], v225 offset:43008
	ds_read_b64_tr_b16 v[38:39], v225 offset:43520
	ds_read_b64_tr_b16 v[72:73], v225 offset:44032
	ds_read_b64_tr_b16 v[74:75], v225 offset:44544
	s_waitcnt lgkmcnt(5)
	s_waitcnt lgkmcnt(4)
	ds_read_b128 v[148:151], v210 offset:8704
	ds_read_b128 v[152:155], v210 offset:8736
	ds_read_b128 v[156:159], v210 offset:8768
	ds_read_b128 v[160:163], v210 offset:8800
	s_waitcnt lgkmcnt(3)
	v_mfma_f32_32x32x16_bf16 v[92:107], v[148:151], v[176:179], 0
	ds_read_b128 v[148:151], v210 offset:8832
	v_sub_f32_e32 v234, v250, v234
	v_sub_f32_e32 v235, v250, v235
	v_sub_f32_e32 v236, v250, v236
	v_sub_f32_e32 v237, v250, v237
	v_sub_f32_e32 v238, v250, v238
	v_sub_f32_e32 v239, v250, v239
	v_sub_f32_e32 v240, v250, v240
	v_sub_f32_e32 v241, v250, v241
	v_sub_f32_e32 v242, v250, v242
	s_waitcnt lgkmcnt(3)
	v_mfma_f32_32x32x16_bf16 v[92:107], v[152:155], v[180:183], v[92:107]
	ds_read_b128 v[152:155], v210 offset:8864
	v_sub_f32_e32 v243, v250, v243
	v_sub_f32_e32 v244, v250, v244
	v_sub_f32_e32 v245, v250, v245
	v_sub_f32_e32 v246, v250, v246
	v_sub_f32_e32 v247, v250, v247
	v_sub_f32_e32 v248, v250, v248
	v_sub_f32_e32 v249, v250, v249
	v_exp_f32_e32 v234, v234
	v_exp_f32_e32 v235, v235
	s_waitcnt lgkmcnt(3)
	v_mfma_f32_32x32x16_bf16 v[92:107], v[156:159], v[184:187], v[92:107]
	ds_read_b128 v[156:159], v210 offset:8896
	v_exp_f32_e32 v236, v236
	v_exp_f32_e32 v237, v237
	v_exp_f32_e32 v238, v238
	v_exp_f32_e32 v239, v239
	v_exp_f32_e32 v240, v240
	v_exp_f32_e32 v241, v241
	v_exp_f32_e32 v242, v242
	v_exp_f32_e32 v243, v243
	v_exp_f32_e32 v244, v244
	s_waitcnt lgkmcnt(3)
	v_mfma_f32_32x32x16_bf16 v[92:107], v[160:163], v[188:191], v[92:107]
	ds_read_b128 v[160:163], v210 offset:8928
	v_exp_f32_e32 v245, v245
	v_exp_f32_e32 v246, v246
	v_exp_f32_e32 v247, v247
	v_exp_f32_e32 v248, v248
	v_exp_f32_e32 v249, v249
	v_mul_f32_e32 v116, v116, v234
	v_mul_f32_e32 v117, v117, v235
	v_mul_f32_e32 v118, v118, v236
	v_mul_f32_e32 v119, v119, v237
	s_waitcnt lgkmcnt(3)
	v_mfma_f32_32x32x16_bf16 v[92:107], v[148:151], v[192:195], v[92:107]
	v_mul_f32_e32 v120, v120, v238
	v_mul_f32_e32 v121, v121, v239
	v_mul_f32_e32 v122, v122, v240
	v_mul_f32_e32 v123, v123, v241
	v_mul_f32_e32 v124, v124, v242
	v_mul_f32_e32 v125, v125, v243
	v_mul_f32_e32 v126, v126, v244
	v_mul_f32_e32 v127, v127, v245
	v_mul_f32_e32 v128, v128, v246
	s_waitcnt lgkmcnt(2)
	v_mfma_f32_32x32x16_bf16 v[92:107], v[152:155], v[196:199], v[92:107]
	v_mul_f32_e32 v129, v129, v247
	v_mul_f32_e32 v130, v130, v248
	v_mul_f32_e32 v131, v131, v249
	v_cndmask_b32_e64 v116, 0, v116, s[64:65]
	v_cndmask_b32_e64 v117, 0, v117, s[66:67]
	v_cndmask_b32_e64 v118, 0, v118, s[68:69]
	v_cndmask_b32_e64 v119, 0, v119, s[70:71]
	v_cndmask_b32_e64 v120, 0, v120, s[72:73]
	v_cndmask_b32_e64 v121, 0, v121, s[74:75]
	s_waitcnt lgkmcnt(1)
	v_mfma_f32_32x32x16_bf16 v[92:107], v[156:159], v[200:203], v[92:107]
	v_cndmask_b32_e64 v122, 0, v122, s[76:77]
	v_cndmask_b32_e64 v123, 0, v123, s[78:79]
	v_cndmask_b32_e64 v124, 0, v124, s[80:81]
	v_cndmask_b32_e64 v125, 0, v125, s[82:83]
	v_cndmask_b32_e64 v126, 0, v126, s[84:85]
	v_cndmask_b32_e64 v127, 0, v127, s[86:87]
	v_cndmask_b32_e64 v128, 0, v128, s[88:89]
	v_cndmask_b32_e64 v129, 0, v129, s[90:91]
	v_cndmask_b32_e64 v130, 0, v130, s[92:93]
	s_waitcnt lgkmcnt(0)
	v_mfma_f32_32x32x16_bf16 v[92:107], v[160:163], v[204:207], v[92:107]
	v_cndmask_b32_e64 v131, 0, v131, s[94:95]
	v_cvt_pk_bf16_f32 v116, v116, v117
	v_cvt_pk_bf16_f32 v117, v118, v119
	v_cvt_pk_bf16_f32 v118, v120, v121
	v_cvt_pk_bf16_f32 v119, v122, v123
	v_cvt_pk_bf16_f32 v120, v124, v125
	v_cvt_pk_bf16_f32 v121, v126, v127
	v_cvt_pk_bf16_f32 v122, v128, v129
	v_cvt_pk_bf16_f32 v123, v130, v131
	v_mfma_f32_32x32x16_bf16 v[76:91], v[36:39], v[116:119], 0
	v_mfma_f32_32x32x16_bf16 v[76:91], v[72:75], v[120:123], v[76:91]
	s_branch .Lm_ydone_30
.Lm_yfin2_28:
	ds_read_b64_tr_b16 v[36:37], v225 offset:43008
	ds_read_b64_tr_b16 v[38:39], v225 offset:43520
	ds_read_b64_tr_b16 v[72:73], v225 offset:44032
	ds_read_b64_tr_b16 v[74:75], v225 offset:44544
	s_waitcnt lgkmcnt(4)
	ds_read_b128 v[148:151], v210 offset:8704
	ds_read_b128 v[152:155], v210 offset:8736
	ds_read_b128 v[156:159], v210 offset:8768
	ds_read_b128 v[160:163], v210 offset:8800
	s_waitcnt lgkmcnt(3)
	v_mfma_f32_32x32x16_bf16 v[92:107], v[148:151], v[176:179], 0
	ds_read_b128 v[148:151], v210 offset:8832
	v_sub_f32_e32 v234, v250, v234
	v_sub_f32_e32 v235, v250, v235
	v_sub_f32_e32 v236, v250, v236
	v_sub_f32_e32 v237, v250, v237
	v_sub_f32_e32 v238, v250, v238
	v_sub_f32_e32 v239, v250, v239
	v_sub_f32_e32 v240, v250, v240
	s_waitcnt lgkmcnt(3)
	v_mfma_f32_32x32x16_bf16 v[92:107], v[152:155], v[180:183], v[92:107]
	ds_read_b128 v[152:155], v210 offset:8864
	v_sub_f32_e32 v241, v250, v241
	v_sub_f32_e32 v242, v250, v242
	v_sub_f32_e32 v243, v250, v243
	v_sub_f32_e32 v244, v250, v244
	v_sub_f32_e32 v245, v250, v245
	v_sub_f32_e32 v246, v250, v246
	v_sub_f32_e32 v247, v250, v247
	s_waitcnt lgkmcnt(3)
	v_mfma_f32_32x32x16_bf16 v[92:107], v[156:159], v[184:187], v[92:107]
	ds_read_b128 v[156:159], v210 offset:8896
	v_sub_f32_e32 v248, v250, v248
	v_sub_f32_e32 v249, v250, v249
	v_exp_f32_e32 v234, v234
	v_exp_f32_e32 v235, v235
	v_exp_f32_e32 v236, v236
	v_exp_f32_e32 v237, v237
	v_exp_f32_e32 v238, v238
	s_waitcnt lgkmcnt(3)
	v_mfma_f32_32x32x16_bf16 v[92:107], v[160:163], v[188:191], v[92:107]
	ds_read_b128 v[160:163], v210 offset:8928
	v_exp_f32_e32 v239, v239
	v_exp_f32_e32 v240, v240
	v_exp_f32_e32 v241, v241
	v_exp_f32_e32 v242, v242
	v_exp_f32_e32 v243, v243
	v_exp_f32_e32 v244, v244
	v_exp_f32_e32 v245, v245
	s_waitcnt lgkmcnt(3)
	v_mfma_f32_32x32x16_bf16 v[92:107], v[148:151], v[192:195], v[92:107]
	v_exp_f32_e32 v246, v246
	v_exp_f32_e32 v247, v247
	v_exp_f32_e32 v248, v248
	v_exp_f32_e32 v249, v249
	v_mul_f32_e32 v132, v132, v234
	v_mul_f32_e32 v133, v133, v235
	v_mul_f32_e32 v134, v134, v236
	s_waitcnt lgkmcnt(2)
	v_mfma_f32_32x32x16_bf16 v[92:107], v[152:155], v[196:199], v[92:107]
	v_mul_f32_e32 v135, v135, v237
	v_mul_f32_e32 v136, v136, v238
	v_mul_f32_e32 v137, v137, v239
	v_mul_f32_e32 v138, v138, v240
	v_mul_f32_e32 v139, v139, v241
	v_mul_f32_e32 v140, v140, v242
	v_mul_f32_e32 v141, v141, v243
	s_waitcnt lgkmcnt(1)
	v_mfma_f32_32x32x16_bf16 v[92:107], v[156:159], v[200:203], v[92:107]
	v_mul_f32_e32 v142, v142, v244
	v_mul_f32_e32 v143, v143, v245
	v_mul_f32_e32 v144, v144, v246
	v_mul_f32_e32 v145, v145, v247
	v_mul_f32_e32 v146, v146, v248
	v_mul_f32_e32 v147, v147, v249
	v_cvt_pk_bf16_f32 v132, v132, v133
	s_waitcnt lgkmcnt(0)
	v_mfma_f32_32x32x16_bf16 v[92:107], v[160:163], v[204:207], v[92:107]
	v_cvt_pk_bf16_f32 v133, v134, v135
	v_cvt_pk_bf16_f32 v134, v136, v137
	v_cvt_pk_bf16_f32 v135, v138, v139
	v_cvt_pk_bf16_f32 v136, v140, v141
	v_cvt_pk_bf16_f32 v137, v142, v143
	v_cvt_pk_bf16_f32 v138, v144, v145
	v_cvt_pk_bf16_f32 v139, v146, v147
	v_mfma_f32_32x32x16_bf16 v[76:91], v[36:39], v[132:135], v[76:91]
	v_mfma_f32_32x32x16_bf16 v[76:91], v[72:75], v[136:139], v[76:91]
	s_branch .Lm_ydone_30
.Lm_yfin3_29:
	ds_read_b64_tr_b16 v[36:37], v225 offset:43008
	ds_read_b64_tr_b16 v[38:39], v225 offset:43520
	ds_read_b64_tr_b16 v[72:73], v225 offset:44032
	ds_read_b64_tr_b16 v[74:75], v225 offset:44544
	s_waitcnt lgkmcnt(4)
	ds_read_b128 v[148:151], v210 offset:8704
	ds_read_b128 v[152:155], v210 offset:8736
	ds_read_b128 v[156:159], v210 offset:8768
	ds_read_b128 v[160:163], v210 offset:8800
	s_waitcnt lgkmcnt(3)
	v_mfma_f32_32x32x16_bf16 v[92:107], v[148:151], v[176:179], 0
	ds_read_b128 v[148:151], v210 offset:8832
	v_sub_f32_e32 v234, v250, v234
	v_sub_f32_e32 v235, v250, v235
	v_sub_f32_e32 v236, v250, v236
	v_sub_f32_e32 v237, v250, v237
	v_sub_f32_e32 v238, v250, v238
	v_sub_f32_e32 v239, v250, v239
	v_sub_f32_e32 v240, v250, v240
	s_waitcnt lgkmcnt(3)
	v_mfma_f32_32x32x16_bf16 v[92:107], v[152:155], v[180:183], v[92:107]
	ds_read_b128 v[152:155], v210 offset:8864
	v_sub_f32_e32 v241, v250, v241
	v_sub_f32_e32 v242, v250, v242
	v_sub_f32_e32 v243, v250, v243
	v_sub_f32_e32 v244, v250, v244
	v_sub_f32_e32 v245, v250, v245
	v_sub_f32_e32 v246, v250, v246
	v_sub_f32_e32 v247, v250, v247
	s_waitcnt lgkmcnt(3)
	v_mfma_f32_32x32x16_bf16 v[92:107], v[156:159], v[184:187], v[92:107]
	ds_read_b128 v[156:159], v210 offset:8896
	v_sub_f32_e32 v248, v250, v248
	v_sub_f32_e32 v249, v250, v249
	v_exp_f32_e32 v234, v234
	v_exp_f32_e32 v235, v235
	v_exp_f32_e32 v236, v236
	v_exp_f32_e32 v237, v237
	v_exp_f32_e32 v238, v238
	s_waitcnt lgkmcnt(3)
	v_mfma_f32_32x32x16_bf16 v[92:107], v[160:163], v[188:191], v[92:107]
	ds_read_b128 v[160:163], v210 offset:8928
	v_exp_f32_e32 v239, v239
	v_exp_f32_e32 v240, v240
	v_exp_f32_e32 v241, v241
	v_exp_f32_e32 v242, v242
	v_exp_f32_e32 v243, v243
	v_exp_f32_e32 v244, v244
	v_exp_f32_e32 v245, v245
	s_waitcnt lgkmcnt(3)
	v_mfma_f32_32x32x16_bf16 v[92:107], v[148:151], v[192:195], v[92:107]
	v_exp_f32_e32 v246, v246
	v_exp_f32_e32 v247, v247
	v_exp_f32_e32 v248, v248
	v_exp_f32_e32 v249, v249
	v_mul_f32_e32 v116, v116, v234
	v_mul_f32_e32 v117, v117, v235
	v_mul_f32_e32 v118, v118, v236
	s_waitcnt lgkmcnt(2)
	v_mfma_f32_32x32x16_bf16 v[92:107], v[152:155], v[196:199], v[92:107]
	v_mul_f32_e32 v119, v119, v237
	v_mul_f32_e32 v120, v120, v238
	v_mul_f32_e32 v121, v121, v239
	v_mul_f32_e32 v122, v122, v240
	v_mul_f32_e32 v123, v123, v241
	v_mul_f32_e32 v124, v124, v242
	v_mul_f32_e32 v125, v125, v243
	s_waitcnt lgkmcnt(1)
	v_mfma_f32_32x32x16_bf16 v[92:107], v[156:159], v[200:203], v[92:107]
	v_mul_f32_e32 v126, v126, v244
	v_mul_f32_e32 v127, v127, v245
	v_mul_f32_e32 v128, v128, v246
	v_mul_f32_e32 v129, v129, v247
	v_mul_f32_e32 v130, v130, v248
	v_mul_f32_e32 v131, v131, v249
	v_cvt_pk_bf16_f32 v116, v116, v117
	s_waitcnt lgkmcnt(0)
	v_mfma_f32_32x32x16_bf16 v[92:107], v[160:163], v[204:207], v[92:107]
	v_cvt_pk_bf16_f32 v117, v118, v119
	v_cvt_pk_bf16_f32 v118, v120, v121
	v_cvt_pk_bf16_f32 v119, v122, v123
	v_cvt_pk_bf16_f32 v120, v124, v125
	v_cvt_pk_bf16_f32 v121, v126, v127
	v_cvt_pk_bf16_f32 v122, v128, v129
	v_cvt_pk_bf16_f32 v123, v130, v131
	v_mfma_f32_32x32x16_bf16 v[76:91], v[36:39], v[116:119], v[76:91]
	v_mfma_f32_32x32x16_bf16 v[76:91], v[72:75], v[120:123], v[76:91]

.Lm_hi_24:
	ds_read_b32 v1, v172 offset:2048
	ds_read_b64_tr_b16 v[116:117], v193 offset:0
	ds_read_b64_tr_b16 v[118:119], v193 offset:1088
	ds_read_b64_tr_b16 v[120:121], v192 offset:0
	ds_read_b64_tr_b16 v[122:123], v192 offset:256
	ds_read_b64_tr_b16 v[124:125], v193 offset:4352
	ds_read_b64_tr_b16 v[126:127], v193 offset:5440
	ds_read_b64_tr_b16 v[128:129], v192 offset:1024
	ds_read_b64_tr_b16 v[130:131], v192 offset:1280
	ds_read_b64_tr_b16 v[132:133], v193 offset:8704
	ds_read_b64_tr_b16 v[134:135], v193 offset:9792
	ds_read_b64_tr_b16 v[136:137], v192 offset:2048
	ds_read_b64_tr_b16 v[138:139], v192 offset:2304
	s_waitcnt lgkmcnt(12)
	v_exp_f32_e32 v1, v1
	s_nop 0
	v_mul_f32_e32 v176, v176, v1
	v_mul_f32_e32 v177, v177, v1
	v_mul_f32_e32 v178, v178, v1
	v_mul_f32_e32 v179, v179, v1
	v_mul_f32_e32 v180, v180, v1
	v_mul_f32_e32 v181, v181, v1
	v_mul_f32_e32 v182, v182, v1
	v_mul_f32_e32 v183, v183, v1
	v_mul_f32_e32 v184, v184, v1
	v_mul_f32_e32 v185, v185, v1
	v_mul_f32_e32 v186, v186, v1
	v_mul_f32_e32 v187, v187, v1
	v_mul_f32_e32 v188, v188, v1
	v_mul_f32_e32 v189, v189, v1
	v_mul_f32_e32 v190, v190, v1
	v_mul_f32_e32 v191, v191, v1
	s_nop 1
	s_waitcnt lgkmcnt(8)
	v_mfma_f32_32x32x16_bf16 v[176:191], v[116:119], v[120:123], v[176:191]
	ds_read_b64_tr_b16 v[116:117], v193 offset:13056
	ds_read_b64_tr_b16 v[118:119], v193 offset:14144
	ds_read_b64_tr_b16 v[120:121], v192 offset:3072
	ds_read_b64_tr_b16 v[122:123], v192 offset:3328
	global_load_dwordx4 v[40:43], v164, s[38:39]
	s_waitcnt lgkmcnt(8)
	v_mfma_f32_32x32x16_bf16 v[176:191], v[124:127], v[128:131], v[176:191]
	ds_read_b64_tr_b16 v[124:125], v193 offset:17408
	ds_read_b64_tr_b16 v[126:127], v193 offset:18496
	ds_read_b64_tr_b16 v[128:129], v192 offset:4096
	ds_read_b64_tr_b16 v[130:131], v192 offset:4352
	global_load_dwordx4 v[56:59], v164, s[38:39] offset:256
	s_waitcnt lgkmcnt(8)
	v_mfma_f32_32x32x16_bf16 v[176:191], v[132:135], v[136:139], v[176:191]
	ds_read_b64_tr_b16 v[132:133], v193 offset:21760
	ds_read_b64_tr_b16 v[134:135], v193 offset:22848
	ds_read_b64_tr_b16 v[136:137], v192 offset:5120
	ds_read_b64_tr_b16 v[138:139], v192 offset:5376
	global_load_dwordx4 v[44:47], v165, s[38:39]
	s_waitcnt lgkmcnt(8)
	v_mfma_f32_32x32x16_bf16 v[176:191], v[116:119], v[120:123], v[176:191]
	ds_read_b64_tr_b16 v[116:117], v193 offset:26112
	ds_read_b64_tr_b16 v[118:119], v193 offset:27200
	ds_read_b64_tr_b16 v[120:121], v192 offset:6144
	ds_read_b64_tr_b16 v[122:123], v192 offset:6400
	global_load_dwordx4 v[60:63], v165, s[38:39] offset:256
	s_waitcnt lgkmcnt(8)
	v_mfma_f32_32x32x16_bf16 v[176:191], v[124:127], v[128:131], v[176:191]
	ds_read_b64_tr_b16 v[124:125], v193 offset:30464
	ds_read_b64_tr_b16 v[126:127], v193 offset:31552
	ds_read_b64_tr_b16 v[128:129], v192 offset:7168
	ds_read_b64_tr_b16 v[130:131], v192 offset:7424
	global_load_dwordx4 v[48:51], v166, s[38:39]
	s_waitcnt lgkmcnt(8)
	v_mfma_f32_32x32x16_bf16 v[176:191], v[132:135], v[136:139], v[176:191]
	global_load_dwordx4 v[64:67], v166, s[38:39] offset:256
	s_waitcnt lgkmcnt(4)
	v_mfma_f32_32x32x16_bf16 v[176:191], v[116:119], v[120:123], v[176:191]
	global_load_dwordx4 v[52:55], v167, s[38:39]
	s_waitcnt lgkmcnt(0)
	v_mfma_f32_32x32x16_bf16 v[176:191], v[124:127], v[128:131], v[176:191]
	global_load_dwordx4 v[68:71], v167, s[38:39] offset:256
	global_load_dwordx4 v[72:75], v168, s[40:41]
	global_load_dwordx4 v[208:211], v202, s[40:41]
	s_add_u32 s38, s38, s46
	s_addc_u32 s39, s39, s55
	s_add_u32 s40, s40, s47
	s_addc_u32 s41, s41, s55
	s_nop 7
	s_nop 3
	v_cvt_pk_bf16_f32 v140, v176, v177
	v_cvt_pk_bf16_f32 v141, v178, v179
	v_cvt_pk_bf16_f32 v142, v180, v181
	v_cvt_pk_bf16_f32 v143, v182, v183
	v_cvt_pk_bf16_f32 v144, v184, v185
	v_cvt_pk_bf16_f32 v145, v186, v187
	v_cvt_pk_bf16_f32 v146, v188, v189
	v_cvt_pk_bf16_f32 v147, v190, v191
	ds_write_b64 v194, v[140:141] offset:0
	ds_write_b64 v194, v[142:143] offset:16
	ds_write_b64 v194, v[144:145] offset:32
	ds_write_b64 v194, v[146:147] offset:48
	s_cmp_eq_u32 s3, 7
	s_cbranch_scc0 .Lm_noscan_26
	s_cmp_lt_u32 s50, 63
	s_cbranch_scc0 .Lm_noscan_26
	s_waitcnt vmcnt(10)
	v_mul_f32_e32 v116, s62, v204
	v_mul_f32_e32 v117, s62, v205
	v_add_f32_e32 v118, v116, v117
	s_nop 1
	v_add_f32_dpp v118, v118, v118 row_shr:1 row_mask:0xf bank_mask:0xf bound_ctrl:0
	s_nop 1
	v_add_f32_dpp v118, v118, v118 row_shr:2 row_mask:0xf bank_mask:0xf bound_ctrl:0
	s_nop 1
	v_add_f32_dpp v118, v118, v118 row_shr:4 row_mask:0xf bank_mask:0xf bound_ctrl:0
	s_nop 1
	v_add_f32_dpp v118, v118, v118 row_shr:8 row_mask:0xf bank_mask:0xf bound_ctrl:0
	s_nop 1
	v_add_f32_dpp v118, v118, v118 row_bcast:15 row_mask:0xa bank_mask:0xf
	s_nop 1
	v_add_f32_dpp v118, v118, v118 row_bcast:31 row_mask:0xc bank_mask:0xf
	s_nop 1
	v_readlane_b32 s97, v118, 63
	v_sub_f32_e32 v122, v118, v117
	v_mov_b32_e32 v123, v118
	s_nop 1
	s_cmp_eq_u32 s51, 0
	s_cbranch_scc1 .Lm_scanf_31
	v_sub_f32_e32 v122, s97, v122
	v_sub_f32_e32 v123, s97, v123
	v_fma_f32 v122, v204, s62, v122
	v_fma_f32 v123, v205, s62, v123

.Lm_noscan_26:
.Lm_adone_25:
	s_waitcnt lgkmcnt(0)
	s_barrier
	s_cmp_lt_u32 s50, 63
	s_cbranch_scc0 .Lm_now_32
	s_cmp_lt_u32 s3, 4
	s_cbranch_scc0 .Lm_whi_36
	s_waitcnt vmcnt(8)
	ds_write_b128 v169, v[20:23] offset:0
	ds_write_b128 v169, v[4:7] offset:34816
	ds_write_b128 v169, v[24:27] offset:8704
	ds_write_b128 v169, v[8:11] offset:43520
	ds_write_b128 v169, v[28:31] offset:17408
	ds_write_b128 v169, v[12:15] offset:52224
	ds_write_b128 v169, v[32:35] offset:26112
	ds_write_b128 v169, v[16:19] offset:60928
	s_branch .Lm_now_32
